# E5B epilogue load hoist distance 5 groups (was 3), otherwise the packed-op-split stack
# speedup vs baseline: 1.0027x; 1.0027x over previous
; DI bf16_t f2bf(float x) { return (bf16_t)(cvt_pk(x, 0.f) & 0xffffu); }
; DI float ex2(float x) { return __builtin_amdgcn_exp2f(x); }
; DI size_t vf_off(int item, int dvh, int j) { return ((size_t)((item * 16 + (dvh >> 5)) * 4 + (j >> 4)) * 64 + ((j >> 3) & 1) * 32 + (dvh & 31)) * 8 + (j & 7); }
;     ...
;         const u32x2 ov = *(const u32x2*)((const bf16_t*)(p.ws + OFF_VT1) + vf_off((((pos + 48) >> 6) * 4 + b) * 4 + (col >> 9), col & 511, (pos + 48) & 63));
;         bf16_t* d = (bf16_t*)(p.ws + OFF_YB) + (size_t)row0 * 2048 + col;
; #pragma unroll
;         for (int e = 0; e < 4; ++e) {
;             const unsigned ob = (e & 1) ? (ov[e >> 1] & 0xffff0000u) : (ov[e >> 1] << 16);
;             const float o = __uint_as_float(ob);
;             const float gte = v[e] / (1.f + __expf(-v[e]));
;             d[(size_t)e * 2048] = f2bf(gte * o * s_aux[lrow0 + e]);
; template <int EPI, int K, int LNI = -1>
; DI void ph_gemm(const Params& p, const bf16_t* __restrict__ A, const bf16_t* __restrict__ Bt, int N, float* s_aux) {
;     ...
;             for (int ai = 0; ai < 2; ++ai)
; #pragma unroll
;                 for (int m = 0; m < 4; ++m) {
;                     const int lrow0 = ai * 128 + wr * 64 + m * 16 + fq * 4, row0 = brow + lrow0 + oz;
;                     f32x2 rs[4];
;                     if (EPI == EPI_RESID && LNI >= 0) {
;                         const f32x2* st_ = (const f32x2*)((unsigned char*)p.out + OFFO_STATS) + row0;
; #pragma unroll
;                         for (int e = 0; e < 4; ++e) rs[e] = st_[e];
;                     }
;                     if (EPI == EPI_E5) {
;                         const int idx_ = ((row0 % LT) + 48) & 63; const float lgh = lg_[0][0];
; #pragma unroll
;                         for (int e = 0; e < 4; ++e) rs[e] = (f32x2){ex2(lgh * (float)(idx_ + e + 1)), 0.0625f * ex2(lgh * (float)(63 - idx_ - e))};
;                     }
; #pragma unroll
;                     for (int bj = 0; bj < 2; ++bj)
; #pragma unroll
;                         for (int n = 0; n < 2; ++n) {
;                             float v[4];
; #pragma unroll
;                             for (int e = 0; e < 4; ++e) v[e] = acc[ai][bj][m][n][e];
;                             epi_store<EPI, LNI>(p, row0, bcol + bj * 128 + wc * 32 + n * 16 + fr + oz, lrow0, v, sa, rs, lg_[bj][n], lb_[bj][n]);
.LBB0_1639:
	s_or_b64 exec, exec, s[12:13]
	v_mov_b32_e32 v128, 0
	v_lshl_or_b32 v129, s10, 8, v181
	v_add_u32_e32 v192, s42, v128
	v_add_u32_e32 v148, v129, v128
	v_add_u32_e32 v128, v128, v172
	v_add_u32_e32 v154, v192, v173
	v_and_b32_e32 v191, 31, v128
	v_mul_hi_i32 v128, v154, s68
	v_lshrrev_b32_e32 v129, 31, v128
	v_ashrrev_i32_e32 v128, 12, v128
	v_add_u32_e32 v128, v128, v129
	v_mul_i32_i24_e32 v129, 0xffffdff0, v128
	v_add3_u32 v129, v154, v129, 48
	v_lshrrev_b32_e32 v130, 4, v129
	v_and_b32_e32 v130, 0xfffffc, v130
	v_add_lshl_u32 v198, v130, v128, 8
	v_lshlrev_b32_e32 v128, 2, v129
	v_and_b32_e32 v196, 32, v128
	v_and_b32_e32 v128, 7, v154
	v_lshlrev_b32_e32 v140, 1, v128
	v_ashrrev_i32_e32 v128, 3, v148
	v_bfe_u32 v197, v129, 4, 2
	v_and_b32_e32 v193, 0xffffffc0, v128
	v_lshrrev_b32_e32 v129, 3, v148
	v_add_u32_e32 v128, v198, v193
	v_and_b32_e32 v194, 60, v129
	v_or3_b32 v128, v128, v194, v197
	v_ashrrev_i32_e32 v129, 31, v128
	v_lshlrev_b64 v[128:129], 6, v[128:129]
	v_lshl_add_u64 v[150:151], s[20:21], 0, v[140:141]
	v_or3_b32 v128, v128, v196, v191
	v_lshl_add_u64 v[128:129], v[128:129], 4, v[150:151]
	global_load_dwordx2 v[152:153], v[128:129], off
	v_mul_f32_e32 v128, 0xbfb8aa3b, v124
	v_mul_f32_e32 v129, 0xbfb8aa3b, v125
	v_exp_f32_e32 v140, v128
	v_exp_f32_e32 v156, v129
	v_ashrrev_i32_e32 v149, 31, v148
	v_lshl_add_u32 v195, v173, 2, s11
	v_add_f32_e32 v140, 1.0, v140
	v_lshlrev_b64 v[146:147], 1, v[148:149]
	v_add_f32_e32 v149, 1.0, v156
	v_mul_f32_e32 v130, 0xbfb8aa3b, v126
	v_exp_f32_e32 v157, v130
	s_nop 0
	v_add_f32_e32 v199, 1.0, v157
	ds_read_b128 v[132:135], v195
	ds_read_b128 v[128:131], v195 offset:64
	s_mov_b64 vcc, s[10:11]
	v_ashrrev_i32_e32 v155, 31, v154
	v_rcp_f32_e32 v200, v140
	s_nop 0
	v_mul_f32_e32 v124, v124, v200
	v_lshlrev_b64 v[154:155], 12, v[154:155]
	v_rcp_f32_e32 v140, v149
	s_nop 0
	v_mul_f32_e32 v125, v125, v140
	v_lshl_add_u64 v[154:155], s[36:37], 0, v[154:155]
	v_lshl_add_u64 v[156:157], v[154:155], 0, v[146:147]
	v_add_co_u32_e64 v154, s[14:15], s3, v156
	s_nop 1
	v_addc_co_u32_e64 v155, s[14:15], 0, v157, s[14:15]
	s_mov_b64 vcc, s[12:13]
	s_waitcnt vmcnt(0)
	v_add_u32_e32 v228, 16, v148
	v_ashrrev_i32_e32 v229, 3, v228
	v_and_b32_e32 v229, 0xffffffc0, v229
	v_lshrrev_b32_e32 v230, 3, v228
	v_add_u32_e32 v231, v198, v229
	v_and_b32_e32 v230, 60, v230
	v_or3_b32 v232, v231, v230, v197
	v_ashrrev_i32_e32 v233, 31, v232
	v_lshlrev_b64 v[232:233], 6, v[232:233]
	v_and_b32_e32 v228, 31, v228
	v_or3_b32 v232, v232, v196, v228
	v_lshl_add_u64 v[232:233], v[232:233], 4, v[150:151]
	global_load_dwordx2 v[218:219], v[232:233], off
	v_add_u32_e32 v228, 0x80, v148
	v_ashrrev_i32_e32 v229, 3, v228
	v_and_b32_e32 v229, 0xffffffc0, v229
	v_lshrrev_b32_e32 v228, 3, v228
	v_add_u32_e32 v230, v198, v229
	v_and_b32_e32 v231, 60, v228
	v_or3_b32 v232, v230, v231, v197
	v_ashrrev_i32_e32 v233, 31, v232
	v_lshlrev_b64 v[232:233], 6, v[232:233]
	v_or3_b32 v232, v232, v196, v191
	v_lshl_add_u64 v[232:233], v[232:233], 4, v[150:151]
	global_load_dwordx2 v[220:221], v[232:233], off
	v_add_u32_e32 v228, 0x90, v148
	v_ashrrev_i32_e32 v230, 3, v228
	v_and_b32_e32 v229, 0xffffffc0, v230
	v_lshrrev_b32_e32 v231, 3, v228
	v_add_u32_e32 v230, v198, v229
	v_and_b32_e32 v232, 60, v231
	v_or3_b32 v230, v230, v232, v197
	v_ashrrev_i32_e32 v231, 31, v230
	v_lshlrev_b64 v[230:231], 6, v[230:231]
	v_and_b32_e32 v228, 31, v228
	v_or3_b32 v230, v230, v196, v228
	v_lshl_add_u64 v[230:231], v[230:231], 4, v[150:151]
	global_load_dwordx2 v[222:223], v[230:231], off
	v_mov_b32_e32 v237, v141
	v_add_u32_e32 v228, v192, v174
	v_mul_hi_i32 v229, v228, s68
	v_lshrrev_b32_e32 v230, 31, v229
	v_ashrrev_i32_e32 v229, 12, v229
	v_add_u32_e32 v229, v229, v230
	v_mul_i32_i24_e32 v230, 0xffffdff0, v229
	v_add3_u32 v230, v228, v230, 48
	v_lshrrev_b32_e32 v231, 4, v230
	v_and_b32_e32 v231, 0xfffffc, v231
	v_add_lshl_u32 v232, v231, v229, 8
	v_lshlrev_b32_e32 v229, 2, v230
	v_and_b32_e32 v233, 32, v229
	v_and_b32_e32 v229, 7, v228
	v_bfe_u32 v234, v230, 4, 2
	v_lshlrev_b32_e32 v236, 1, v229
	v_add_u32_e32 v229, v232, v193
	v_or3_b32 v238, v229, v194, v234
	v_ashrrev_i32_e32 v239, 31, v238
	v_lshlrev_b64 v[238:239], 6, v[238:239]
	v_lshl_add_u64 v[230:231], s[20:21], 0, v[236:237]
	v_or3_b32 v238, v238, v233, v191
	v_lshl_add_u64 v[238:239], v[238:239], 4, v[230:231]
	global_load_dwordx2 v[224:225], v[238:239], off
	v_mov_b32_e32 v239, v141
	v_add_u32_e32 v228, 16, v148
	v_ashrrev_i32_e32 v229, 3, v228
	v_and_b32_e32 v229, 0xffffffc0, v229
	v_lshrrev_b32_e32 v230, 3, v228
	v_and_b32_e32 v230, 60, v230
	v_and_b32_e32 v228, 31, v228
	v_add_u32_e32 v231, v192, v174
	v_mul_hi_i32 v232, v231, s68
	v_lshrrev_b32_e32 v234, 31, v232
	v_ashrrev_i32_e32 v232, 12, v232
	v_add_u32_e32 v232, v232, v234
	v_mul_i32_i24_e32 v234, 0xffffdff0, v232
	v_add3_u32 v234, v231, v234, 48
	v_lshrrev_b32_e32 v235, 4, v234
	v_and_b32_e32 v235, 0xfffffc, v235
	v_add_lshl_u32 v233, v235, v232, 8
	v_lshlrev_b32_e32 v232, 2, v234
	v_and_b32_e32 v236, 32, v232
	v_and_b32_e32 v232, 7, v231
	v_bfe_u32 v237, v234, 4, 2
	v_lshlrev_b32_e32 v238, 1, v232
	v_lshl_add_u64 v[234:235], s[20:21], 0, v[238:239]
	v_add_u32_e32 v240, v233, v229
	v_or3_b32 v240, v240, v230, v237
	v_ashrrev_i32_e32 v241, 31, v240
	v_lshlrev_b64 v[240:241], 6, v[240:241]
	v_or3_b32 v240, v240, v236, v228
	v_lshl_add_u64 v[240:241], v[240:241], 4, v[234:235]
	global_load_dwordx2 v[226:227], v[240:241], off
	v_lshlrev_b32_e32 v140, 16, v152
	v_and_b32_e32 v149, 0xffff0000, v152
	v_mul_f32_e32 v124, v124, v140
	v_mul_f32_e32 v125, v125, v149
	s_waitcnt lgkmcnt(1)
; DI bf16_t f2bf(float x) { return (bf16_t)(cvt_pk(x, 0.f) & 0xffffu); }
; DI size_t vf_off(int item, int dvh, int j) { return ((size_t)((item * 16 + (dvh >> 5)) * 4 + (j >> 4)) * 64 + ((j >> 3) & 1) * 32 + (dvh & 31)) * 8 + (j & 7); }
;     ...
;         const u32x2 ov = *(const u32x2*)((const bf16_t*)(p.ws + OFF_VT1) + vf_off((((pos + 48) >> 6) * 4 + b) * 4 + (col >> 9), col & 511, (pos + 48) & 63));
;         bf16_t* d = (bf16_t*)(p.ws + OFF_YB) + (size_t)row0 * 2048 + col;
; #pragma unroll
;         for (int e = 0; e < 4; ++e) {
;             const unsigned ob = (e & 1) ? (ov[e >> 1] & 0xffff0000u) : (ov[e >> 1] << 16);
;             const float o = __uint_as_float(ob);
;             const float gte = v[e] / (1.f + __expf(-v[e]));
;             d[(size_t)e * 2048] = f2bf(gte * o * s_aux[lrow0 + e]);
; template <int EPI, int K, int LNI = -1>
; DI void ph_gemm(const Params& p, const bf16_t* __restrict__ A, const bf16_t* __restrict__ Bt, int N, float* s_aux) {
;     ...
; #pragma unroll
;                     for (int bj = 0; bj < 2; ++bj)
; #pragma unroll
;                         for (int n = 0; n < 2; ++n) {
;                             float v[4];
; #pragma unroll
;                             for (int e = 0; e < 4; ++e) v[e] = acc[ai][bj][m][n][e];
;                             epi_store<EPI, LNI>(p, row0, bcol + bj * 128 + wc * 32 + n * 16 + fr + oz, lrow0, v, sa, rs, lg_[bj][n], lb_[bj][n]);
	v_mul_f32_e32 v124, v132, v124
	v_mul_f32_e32 v125, v133, v125
	v_cvt_pk_bf16_f32 v124, v124, s0
	v_cvt_pk_bf16_f32 v125, v125, s0
	global_store_short v[156:157], v124, off
	global_store_short v[154:155], v125, off offset:-4096
	v_mul_f32_e32 v125, 0xbfb8aa3b, v127
	v_exp_f32_e32 v125, v125
	s_nop 0
	v_add_f32_e32 v125, 1.0, v125
	v_rcp_f32_e32 v124, v199
	s_nop 0
	v_mul_f32_e32 v124, v126, v124
	v_lshlrev_b32_e32 v152, 16, v153
	v_mul_f32_e32 v124, v124, v152
	v_mul_f32_e32 v124, v134, v124
	v_cvt_pk_bf16_f32 v124, v124, s0
	global_store_short v[154:155], v124, off
	v_and_b32_e32 v124, 0xffff0000, v153
	v_rcp_f32_e32 v126, v125
	s_nop 0
	v_mul_f32_e32 v125, v127, v126
	v_mul_f32_e32 v124, v125, v124
	v_mul_f32_e32 v124, v135, v124
	v_cvt_pk_bf16_f32 v126, v124, s0
	v_add_co_u32_e32 v124, vcc, s69, v156
	v_add_u32_e32 v127, 16, v148
	s_nop 0
	v_addc_co_u32_e32 v125, vcc, 0, v157, vcc
	global_store_short v[124:125], v126, off
	v_ashrrev_i32_e32 v126, 3, v127
	v_and_b32_e32 v126, 0xffffffc0, v126
	v_lshrrev_b32_e32 v149, 3, v127
	v_add_u32_e32 v140, v198, v126
	v_and_b32_e32 v149, 60, v149
	v_or3_b32 v152, v140, v149, v197
	v_ashrrev_i32_e32 v153, 31, v152
	v_lshlrev_b64 v[152:153], 6, v[152:153]
	v_and_b32_e32 v127, 31, v127
	v_or3_b32 v152, v152, v196, v127
	v_lshl_add_u64 v[152:153], v[152:153], 4, v[150:151]
	v_mul_f32_e32 v140, 0xbfb8aa3b, v120
	v_exp_f32_e32 v140, v140
	v_mul_f32_e32 v199, 0xbfb8aa3b, v121
	v_exp_f32_e32 v199, v199
	v_add_f32_e32 v140, 1.0, v140
	v_add_f32_e32 v199, 1.0, v199
	v_rcp_f32_e32 v202, v140
	s_nop 0
	v_mul_f32_e32 v120, v120, v202
	v_add_co_u32_e64 v200, s[10:11], s61, v156
	s_waitcnt vmcnt(8)
	v_mov_b32_e32 v239, v141
	v_add_u32_e32 v228, 0x80, v148
	v_ashrrev_i32_e32 v229, 3, v228
	v_and_b32_e32 v229, 0xffffffc0, v229
	v_lshrrev_b32_e32 v228, 3, v228
	v_and_b32_e32 v230, 60, v228
	v_add_u32_e32 v231, v192, v174
	v_mul_hi_i32 v232, v231, s68
	v_lshrrev_b32_e32 v234, 31, v232
	v_ashrrev_i32_e32 v232, 12, v232
	v_add_u32_e32 v232, v232, v234
	v_mul_i32_i24_e32 v234, 0xffffdff0, v232
	v_add3_u32 v234, v231, v234, 48
	v_lshrrev_b32_e32 v235, 4, v234
	v_and_b32_e32 v235, 0xfffffc, v235
	v_add_lshl_u32 v233, v235, v232, 8
	v_lshlrev_b32_e32 v232, 2, v234
	v_and_b32_e32 v236, 32, v232
	v_and_b32_e32 v232, 7, v231
	v_bfe_u32 v237, v234, 4, 2
	v_lshlrev_b32_e32 v238, 1, v232
	v_lshl_add_u64 v[234:235], s[20:21], 0, v[238:239]
	v_add_u32_e32 v240, v233, v229
	v_or3_b32 v240, v240, v230, v237
	v_ashrrev_i32_e32 v241, 31, v240
	v_lshlrev_b64 v[240:241], 6, v[240:241]
	v_or3_b32 v240, v240, v236, v191
	v_lshl_add_u64 v[240:241], v[240:241], 4, v[234:235]
	global_load_dwordx2 v[216:217], v[240:241], off
	v_lshlrev_b32_e32 v140, 16, v218
	v_mul_f32_e32 v120, v120, v140
	v_mul_f32_e32 v120, v132, v120
	v_cvt_pk_bf16_f32 v120, v120, s0
	global_store_short v[156:157], v120, off offset:32
	v_mul_f32_e32 v140, 0xbfb8aa3b, v122
	v_exp_f32_e32 v140, v140
	v_rcp_f32_e32 v120, v199
	s_nop 0
	v_mul_f32_e32 v120, v121, v120
	v_addc_co_u32_e64 v201, s[10:11], 0, v157, s[10:11]
	v_add_f32_e32 v121, 1.0, v140
	v_and_b32_e32 v152, 0xffff0000, v218
	v_mul_f32_e32 v120, v120, v152
	v_mul_f32_e32 v120, v133, v120
	v_cvt_pk_bf16_f32 v120, v120, s0
	global_store_short v[200:201], v120, off offset:32
	v_mul_f32_e32 v152, 0xbfb8aa3b, v123
	v_exp_f32_e32 v152, v152
	v_lshlrev_b32_e32 v120, 16, v219
	v_rcp_f32_e32 v140, v121
	s_nop 0
	v_mul_f32_e32 v121, v122, v140
	v_mul_f32_e32 v120, v121, v120
	v_add_f32_e32 v121, 1.0, v152
	v_mul_f32_e32 v120, v134, v120
	v_cvt_pk_bf16_f32 v120, v120, s0
	global_store_short v[154:155], v120, off offset:32
	v_and_b32_e32 v120, 0xffff0000, v219
	v_rcp_f32_e32 v122, v121
	s_nop 0
	v_mul_f32_e32 v121, v123, v122
	v_mul_f32_e32 v120, v121, v120
	v_mul_f32_e32 v120, v135, v120
	v_cvt_pk_bf16_f32 v120, v120, s0
	global_store_short v[124:125], v120, off offset:32
	v_add_u32_e32 v120, 0x80, v148
	v_ashrrev_i32_e32 v121, 3, v120
	v_and_b32_e32 v121, 0xffffffc0, v121
	v_lshrrev_b32_e32 v120, 3, v120
	v_add_u32_e32 v123, v198, v121
	v_and_b32_e32 v122, 60, v120
	v_or3_b32 v152, v123, v122, v197
	v_ashrrev_i32_e32 v153, 31, v152
	v_lshlrev_b64 v[152:153], 6, v[152:153]
	v_or3_b32 v152, v152, v196, v191
	v_lshl_add_u64 v[152:153], v[152:153], 4, v[150:151]
	v_mul_f32_e32 v120, 0xbfb8aa3b, v116
	v_exp_f32_e32 v120, v120
	s_waitcnt vmcnt(12)
; DI bf16_t f2bf(float x) { return (bf16_t)(cvt_pk(x, 0.f) & 0xffffu); }
; DI float ex2(float x) { return __builtin_amdgcn_exp2f(x); }
; DI size_t vf_off(int item, int dvh, int j) { return ((size_t)((item * 16 + (dvh >> 5)) * 4 + (j >> 4)) * 64 + ((j >> 3) & 1) * 32 + (dvh & 31)) * 8 + (j & 7); }
;     ...
;         const u32x2 ov = *(const u32x2*)((const bf16_t*)(p.ws + OFF_VT1) + vf_off((((pos + 48) >> 6) * 4 + b) * 4 + (col >> 9), col & 511, (pos + 48) & 63));
;         bf16_t* d = (bf16_t*)(p.ws + OFF_YB) + (size_t)row0 * 2048 + col;
; #pragma unroll
;         for (int e = 0; e < 4; ++e) {
;             const unsigned ob = (e & 1) ? (ov[e >> 1] & 0xffff0000u) : (ov[e >> 1] << 16);
;             const float o = __uint_as_float(ob);
;             const float gte = v[e] / (1.f + __expf(-v[e]));
;             d[(size_t)e * 2048] = f2bf(gte * o * s_aux[lrow0 + e]);
; template <int EPI, int K, int LNI = -1>
; DI void ph_gemm(const Params& p, const bf16_t* __restrict__ A, const bf16_t* __restrict__ Bt, int N, float* s_aux) {
;     ...
;             for (int ai = 0; ai < 2; ++ai)
; #pragma unroll
;                 for (int m = 0; m < 4; ++m) {
;                     const int lrow0 = ai * 128 + wr * 64 + m * 16 + fq * 4, row0 = brow + lrow0 + oz;
;                     f32x2 rs[4];
;                     if (EPI == EPI_RESID && LNI >= 0) {
;                         const f32x2* st_ = (const f32x2*)((unsigned char*)p.out + OFFO_STATS) + row0;
; #pragma unroll
;                         for (int e = 0; e < 4; ++e) rs[e] = st_[e];
;                     }
;                     if (EPI == EPI_E5) {
;                         const int idx_ = ((row0 % LT) + 48) & 63; const float lgh = lg_[0][0];
; #pragma unroll
;                         for (int e = 0; e < 4; ++e) rs[e] = (f32x2){ex2(lgh * (float)(idx_ + e + 1)), 0.0625f * ex2(lgh * (float)(63 - idx_ - e))};
;                     }
; #pragma unroll
;                     for (int bj = 0; bj < 2; ++bj)
; #pragma unroll
;                         for (int n = 0; n < 2; ++n) {
;                             float v[4];
; #pragma unroll
;                             for (int e = 0; e < 4; ++e) v[e] = acc[ai][bj][m][n][e];
;                             epi_store<EPI, LNI>(p, row0, bcol + bj * 128 + wc * 32 + n * 16 + fr + oz, lrow0, v, sa, rs, lg_[bj][n], lb_[bj][n]);
	v_mov_b32_e32 v241, v141
	v_add_u32_e32 v228, 0x90, v148
	v_ashrrev_i32_e32 v229, 3, v228
	v_and_b32_e32 v230, 0xffffffc0, v229
	v_lshrrev_b32_e32 v231, 3, v228
	v_and_b32_e32 v232, 60, v231
	v_and_b32_e32 v228, 31, v228
	v_add_u32_e32 v233, v192, v174
	v_mul_hi_i32 v234, v233, s68
	v_lshrrev_b32_e32 v236, 31, v234
	v_ashrrev_i32_e32 v234, 12, v234
	v_add_u32_e32 v234, v234, v236
	v_mul_i32_i24_e32 v236, 0xffffdff0, v234
	v_add3_u32 v236, v233, v236, 48
	v_lshrrev_b32_e32 v237, 4, v236
	v_and_b32_e32 v237, 0xfffffc, v237
	v_add_lshl_u32 v235, v237, v234, 8
	v_lshlrev_b32_e32 v234, 2, v236
	v_and_b32_e32 v238, 32, v234
	v_and_b32_e32 v234, 7, v233
	v_bfe_u32 v239, v236, 4, 2
	v_lshlrev_b32_e32 v240, 1, v234
	v_lshl_add_u64 v[236:237], s[20:21], 0, v[240:241]
	v_add_u32_e32 v242, v235, v230
	v_or3_b32 v242, v242, v232, v239
	v_ashrrev_i32_e32 v243, 31, v242
	v_lshlrev_b64 v[242:243], 6, v[242:243]
	v_or3_b32 v242, v242, v238, v228
	v_lshl_add_u64 v[242:243], v[242:243], 4, v[236:237]
	global_load_dwordx2 v[218:219], v[242:243], off
	v_lshlrev_b32_e32 v204, 16, v220
	v_add_f32_e32 v120, 1.0, v120
	v_mul_f32_e32 v140, 0xbfb8aa3b, v117
	v_exp_f32_e32 v140, v140
	v_rcp_f32_e32 v123, v120
	s_nop 0
	v_mul_f32_e32 v116, v116, v123
	v_mul_f32_e32 v116, v116, v204
	v_mul_f32_e32 v116, v132, v116
	v_add_f32_e32 v120, 1.0, v140
	v_cvt_pk_bf16_f32 v116, v116, s0
	global_store_short v[156:157], v116, off offset:256
	v_and_b32_e32 v116, 0xffff0000, v220
	v_mul_f32_e32 v140, 0xbfb8aa3b, v118
	v_exp_f32_e32 v140, v140
	v_rcp_f32_e32 v123, v120
	s_nop 0
	v_mul_f32_e32 v117, v117, v123
	v_mul_f32_e32 v116, v117, v116
	v_mul_f32_e32 v116, v133, v116
	v_add_f32_e32 v117, 1.0, v140
	v_cvt_pk_bf16_f32 v116, v116, s0
	global_store_short v[200:201], v116, off offset:256
	v_lshlrev_b32_e32 v116, 16, v221
	v_mul_f32_e32 v123, 0xbfb8aa3b, v119
	v_exp_f32_e32 v123, v123
	v_rcp_f32_e32 v120, v117
	s_nop 0
	v_mul_f32_e32 v117, v118, v120
	v_mul_f32_e32 v116, v117, v116
	v_mul_f32_e32 v116, v134, v116
	v_add_f32_e32 v117, 1.0, v123
	v_cvt_pk_bf16_f32 v116, v116, s0
	global_store_short v[154:155], v116, off offset:256
	v_and_b32_e32 v116, 0xffff0000, v221
	v_rcp_f32_e32 v118, v117
	s_nop 0
	v_mul_f32_e32 v117, v119, v118
	v_mul_f32_e32 v116, v117, v116
	v_mul_f32_e32 v116, v135, v116
	v_cvt_pk_bf16_f32 v116, v116, s0
	v_add_u32_e32 v119, 0x90, v148
	global_store_short v[124:125], v116, off offset:256
	v_ashrrev_i32_e32 v116, 3, v119
	v_and_b32_e32 v118, 0xffffffc0, v116
	v_lshrrev_b32_e32 v117, 3, v119
	v_add_u32_e32 v116, v198, v118
	v_and_b32_e32 v120, 60, v117
	v_or3_b32 v116, v116, v120, v197
	v_ashrrev_i32_e32 v117, 31, v116
	v_lshlrev_b64 v[116:117], 6, v[116:117]
	v_and_b32_e32 v119, 31, v119
	v_or3_b32 v116, v116, v196, v119
	v_lshl_add_u64 v[116:117], v[116:117], 4, v[150:151]
	v_mul_f32_e32 v123, 0xbfb8aa3b, v112
	v_exp_f32_e32 v123, v123
	s_waitcnt vmcnt(16)
	v_mov_b32_e32 v237, v141
	v_add_u32_e32 v228, v192, v175
	v_mul_hi_i32 v229, v228, s68
	v_lshrrev_b32_e32 v230, 31, v229
	v_ashrrev_i32_e32 v229, 12, v229
	v_add_u32_e32 v229, v229, v230
	v_mul_i32_i24_e32 v230, 0xffffdff0, v229
	v_add3_u32 v230, v228, v230, 48
	v_lshrrev_b32_e32 v231, 4, v230
	v_and_b32_e32 v231, 0xfffffc, v231
	v_add_lshl_u32 v232, v231, v229, 8
	v_lshlrev_b32_e32 v229, 2, v230
	v_and_b32_e32 v233, 32, v229
	v_and_b32_e32 v229, 7, v228
	v_bfe_u32 v234, v230, 4, 2
	v_lshlrev_b32_e32 v236, 1, v229
	v_add_u32_e32 v229, v232, v193
	v_or3_b32 v230, v229, v194, v234
	v_ashrrev_i32_e32 v231, 31, v230
	v_lshlrev_b64 v[230:231], 6, v[230:231]
	v_lshl_add_u64 v[238:239], s[20:21], 0, v[236:237]
	v_or3_b32 v230, v230, v233, v191
	v_lshl_add_u64 v[230:231], v[230:231], 4, v[238:239]
	global_load_dwordx2 v[220:221], v[230:231], off
	v_lshlrev_b32_e32 v150, 16, v222
	v_add_f32_e32 v123, 1.0, v123
	s_nop 0
	v_mul_f32_e32 v148, 0xbfb8aa3b, v113
	v_exp_f32_e32 v148, v148
	v_rcp_f32_e32 v140, v123
	s_nop 0
	v_mul_f32_e32 v112, v112, v140
	v_mul_f32_e32 v112, v112, v150
	v_mul_f32_e32 v112, v132, v112
	v_add_f32_e32 v123, 1.0, v148
	v_cvt_pk_bf16_f32 v112, v112, s0
	global_store_short v[156:157], v112, off offset:288
	v_and_b32_e32 v112, 0xffff0000, v222
	v_mul_f32_e32 v132, 0xbfb8aa3b, v114
	v_exp_f32_e32 v132, v132
	v_rcp_f32_e32 v116, v123
	s_nop 0
	v_mul_f32_e32 v113, v113, v116
	v_mul_f32_e32 v112, v113, v112
	v_add_f32_e32 v113, 1.0, v132
	v_mul_f32_e32 v112, v133, v112
	v_cvt_pk_bf16_f32 v112, v112, s0
	global_store_short v[200:201], v112, off offset:288
	v_mul_f32_e32 v123, 0xbfb8aa3b, v115
	v_exp_f32_e32 v123, v123
	v_lshlrev_b32_e32 v112, 16, v223
	v_rcp_f32_e32 v116, v113
	s_nop 0
	v_mul_f32_e32 v113, v114, v116
	v_mul_f32_e32 v112, v113, v112
	v_add_f32_e32 v113, 1.0, v123
	v_mul_f32_e32 v112, v134, v112
	v_cvt_pk_bf16_f32 v112, v112, s0
	global_store_short v[154:155], v112, off offset:288
	v_and_b32_e32 v112, 0xffff0000, v223
	v_rcp_f32_e32 v114, v113
	s_nop 0
	v_mul_f32_e32 v113, v115, v114
	v_mul_f32_e32 v112, v113, v112
	v_mul_f32_e32 v112, v135, v112
	v_cvt_pk_bf16_f32 v112, v112, s0
	global_store_short v[124:125], v112, off offset:288
	v_add_u32_e32 v112, v192, v174
	v_mul_hi_i32 v113, v112, s68
	v_lshrrev_b32_e32 v114, 31, v113
	v_ashrrev_i32_e32 v113, 12, v113
	v_add_u32_e32 v113, v113, v114
	v_mul_i32_i24_e32 v114, 0xffffdff0, v113
	v_add3_u32 v114, v112, v114, 48
	v_lshrrev_b32_e32 v115, 4, v114
	v_and_b32_e32 v115, 0xfffffc, v115
	v_add_lshl_u32 v123, v115, v113, 8
	v_lshlrev_b32_e32 v113, 2, v114
	v_and_b32_e32 v133, 32, v113
	v_and_b32_e32 v113, 7, v112
	v_bfe_u32 v132, v114, 4, 2
	v_lshlrev_b32_e32 v140, 1, v113
	v_add_u32_e32 v113, v123, v193
	v_or3_b32 v116, v113, v194, v132
	v_ashrrev_i32_e32 v117, 31, v116
	v_lshlrev_b64 v[116:117], 6, v[116:117]
	v_lshl_add_u64 v[114:115], s[20:21], 0, v[140:141]
	v_or3_b32 v116, v116, v133, v191
	v_lshl_add_u64 v[116:117], v[116:117], 4, v[114:115]
	v_mul_f32_e32 v113, 0xbfb8aa3b, v108
	v_exp_f32_e32 v124, v113
	v_ashrrev_i32_e32 v113, 31, v112
	v_lshlrev_b64 v[112:113], 12, v[112:113]
	v_lshl_add_u64 v[112:113], s[36:37], 0, v[112:113]
	v_add_f32_e32 v124, 1.0, v124
	v_lshl_add_u64 v[112:113], v[112:113], 0, v[146:147]
	v_mul_f32_e32 v134, 0xbfb8aa3b, v109
	v_exp_f32_e32 v134, v134
	v_rcp_f32_e32 v125, v124
	s_nop 0
	v_mul_f32_e32 v108, v108, v125
	v_add_f32_e32 v124, 1.0, v134
	s_waitcnt vmcnt(20)
; DI bf16_t f2bf(float x) { return (bf16_t)(cvt_pk(x, 0.f) & 0xffffu); }
; DI size_t vf_off(int item, int dvh, int j) { return ((size_t)((item * 16 + (dvh >> 5)) * 4 + (j >> 4)) * 64 + ((j >> 3) & 1) * 32 + (dvh & 31)) * 8 + (j & 7); }
;     ...
;         const u32x2 ov = *(const u32x2*)((const bf16_t*)(p.ws + OFF_VT1) + vf_off((((pos + 48) >> 6) * 4 + b) * 4 + (col >> 9), col & 511, (pos + 48) & 63));
;         bf16_t* d = (bf16_t*)(p.ws + OFF_YB) + (size_t)row0 * 2048 + col;
; #pragma unroll
;         for (int e = 0; e < 4; ++e) {
;             const unsigned ob = (e & 1) ? (ov[e >> 1] & 0xffff0000u) : (ov[e >> 1] << 16);
;             const float o = __uint_as_float(ob);
;             const float gte = v[e] / (1.f + __expf(-v[e]));
;             d[(size_t)e * 2048] = f2bf(gte * o * s_aux[lrow0 + e]);
; template <int EPI, int K, int LNI = -1>
; DI void ph_gemm(const Params& p, const bf16_t* __restrict__ A, const bf16_t* __restrict__ Bt, int N, float* s_aux) {
;     ...
; #pragma unroll
;                     for (int bj = 0; bj < 2; ++bj)
; #pragma unroll
;                         for (int n = 0; n < 2; ++n) {
;                             float v[4];
; #pragma unroll
;                             for (int e = 0; e < 4; ++e) v[e] = acc[ai][bj][m][n][e];
;                             epi_store<EPI, LNI>(p, row0, bcol + bj * 128 + wc * 32 + n * 16 + fr + oz, lrow0, v, sa, rs, lg_[bj][n], lb_[bj][n]);
	v_mov_b32_e32 v237, v141
	v_add_u32_e32 v228, v192, v175
	v_mul_hi_i32 v229, v228, s68
	v_lshrrev_b32_e32 v230, 31, v229
	v_ashrrev_i32_e32 v229, 12, v229
	v_add_u32_e32 v229, v229, v230
	v_mul_i32_i24_e32 v230, 0xffffdff0, v229
	v_add3_u32 v230, v228, v230, 48
	v_lshrrev_b32_e32 v231, 4, v230
	v_and_b32_e32 v231, 0xfffffc, v231
	v_add_lshl_u32 v232, v231, v229, 8
	v_lshlrev_b32_e32 v229, 2, v230
	v_and_b32_e32 v233, 32, v229
	v_and_b32_e32 v229, 7, v228
	v_bfe_u32 v234, v230, 4, 2
	v_lshlrev_b32_e32 v236, 1, v229
	v_lshl_add_u64 v[238:239], s[20:21], 0, v[236:237]
	v_add_u32_e32 v240, v232, v126
	v_or3_b32 v240, v240, v149, v234
	v_ashrrev_i32_e32 v241, 31, v240
	v_lshlrev_b64 v[240:241], 6, v[240:241]
	v_or3_b32 v240, v240, v233, v127
	v_lshl_add_u64 v[240:241], v[240:241], 4, v[238:239]
	global_load_dwordx2 v[222:223], v[240:241], off
	v_lshlrev_b32_e32 v135, 16, v224
	v_mul_f32_e32 v108, v108, v135
	s_waitcnt lgkmcnt(0)
	v_mul_f32_e32 v108, v128, v108
	v_cvt_pk_bf16_f32 v108, v108, s0
	global_store_short v[112:113], v108, off
	v_and_b32_e32 v108, 0xffff0000, v224
	v_rcp_f32_e32 v116, v124
	s_nop 0
	v_mul_f32_e32 v109, v109, v116
	v_mul_f32_e32 v116, 0xbfb8aa3b, v110
	v_exp_f32_e32 v116, v116
	v_mul_f32_e32 v108, v109, v108
	v_mul_f32_e32 v108, v129, v108
	v_cvt_pk_bf16_f32 v124, v108, s0
	v_add_f32_e32 v116, 1.0, v116
	v_add_co_u32_e32 v108, vcc, s3, v112
	s_nop 0
	s_nop 0
	v_addc_co_u32_e32 v109, vcc, 0, v113, vcc
	v_mul_f32_e32 v134, 0xbfb8aa3b, v111
	v_exp_f32_e32 v134, v134
	global_store_short v[108:109], v124, off offset:-4096
	v_lshlrev_b32_e32 v124, 16, v225
	v_rcp_f32_e32 v125, v116
	s_nop 0
	v_mul_f32_e32 v110, v110, v125
	v_add_f32_e32 v116, 1.0, v134
	v_mul_f32_e32 v110, v110, v124
	v_mul_f32_e32 v110, v130, v110
	v_cvt_pk_bf16_f32 v110, v110, s0
	global_store_short v[108:109], v110, off
	v_and_b32_e32 v110, 0xffff0000, v225
	v_rcp_f32_e32 v117, v116
	s_nop 0
	v_mul_f32_e32 v111, v111, v117
	v_mul_f32_e32 v110, v111, v110
	v_mul_f32_e32 v110, v131, v110
	v_cvt_pk_bf16_f32 v116, v110, s0
	v_add_co_u32_e32 v110, vcc, s69, v112
	s_nop 1
	v_addc_co_u32_e32 v111, vcc, 0, v113, vcc
	global_store_short v[110:111], v116, off
	v_add_u32_e32 v116, v123, v126
	v_or3_b32 v116, v116, v149, v132
	v_ashrrev_i32_e32 v117, 31, v116
	v_lshlrev_b64 v[116:117], 6, v[116:117]
	v_or3_b32 v116, v116, v133, v127
	v_lshl_add_u64 v[116:117], v[116:117], 4, v[114:115]
	v_mul_f32_e32 v116, 0xbfb8aa3b, v104
	v_exp_f32_e32 v116, v116
	s_waitcnt vmcnt(24)
	v_mov_b32_e32 v237, v141
	v_add_u32_e32 v228, v192, v175
	v_mul_hi_i32 v229, v228, s68
	v_lshrrev_b32_e32 v230, 31, v229
	v_ashrrev_i32_e32 v229, 12, v229
	v_add_u32_e32 v229, v229, v230
	v_mul_i32_i24_e32 v230, 0xffffdff0, v229
	v_add3_u32 v230, v228, v230, 48
	v_lshrrev_b32_e32 v231, 4, v230
	v_and_b32_e32 v231, 0xfffffc, v231
	v_add_lshl_u32 v232, v231, v229, 8
	v_lshlrev_b32_e32 v229, 2, v230
	v_and_b32_e32 v233, 32, v229
	v_and_b32_e32 v229, 7, v228
	v_bfe_u32 v234, v230, 4, 2
	v_lshlrev_b32_e32 v236, 1, v229
	v_lshl_add_u64 v[238:239], s[20:21], 0, v[236:237]
	v_add_u32_e32 v240, v232, v121
	v_or3_b32 v240, v240, v122, v234
	v_ashrrev_i32_e32 v241, 31, v240
	v_lshlrev_b64 v[240:241], 6, v[240:241]
	v_or3_b32 v240, v240, v233, v191
	v_lshl_add_u64 v[240:241], v[240:241], 4, v[238:239]
	global_load_dwordx2 v[224:225], v[240:241], off
	v_lshlrev_b32_e32 v148, 16, v226
	v_add_f32_e32 v134, 1.0, v116
	v_add_co_u32_e32 v116, vcc, s61, v112
	s_nop 0
	s_nop 0
	v_addc_co_u32_e32 v117, vcc, 0, v113, vcc
	v_mul_f32_e32 v140, 0xbfb8aa3b, v105
	v_exp_f32_e32 v140, v140
	v_rcp_f32_e32 v135, v134
	s_nop 0
	v_mul_f32_e32 v104, v104, v135
	v_mul_f32_e32 v104, v104, v148
	v_mul_f32_e32 v104, v128, v104
	v_add_f32_e32 v134, 1.0, v140
	v_cvt_pk_bf16_f32 v104, v104, s0
	global_store_short v[112:113], v104, off offset:32
	v_and_b32_e32 v104, 0xffff0000, v226
	v_mul_f32_e32 v135, 0xbfb8aa3b, v106
	v_exp_f32_e32 v135, v135
	v_rcp_f32_e32 v124, v134
	s_nop 0
	v_mul_f32_e32 v105, v105, v124
	v_mul_f32_e32 v104, v105, v104
	v_add_f32_e32 v105, 1.0, v135
	v_mul_f32_e32 v104, v129, v104
	v_cvt_pk_bf16_f32 v104, v104, s0
	global_store_short v[116:117], v104, off offset:32
	v_mul_f32_e32 v134, 0xbfb8aa3b, v107
	v_exp_f32_e32 v134, v134
	v_lshlrev_b32_e32 v104, 16, v227
	v_rcp_f32_e32 v124, v105
	s_nop 0
	v_mul_f32_e32 v105, v106, v124
	v_mul_f32_e32 v104, v105, v104
	v_add_f32_e32 v105, 1.0, v134
	v_mul_f32_e32 v104, v130, v104
	v_cvt_pk_bf16_f32 v104, v104, s0
	global_store_short v[108:109], v104, off offset:32
	v_and_b32_e32 v104, 0xffff0000, v227
	v_rcp_f32_e32 v106, v105
	s_nop 0
	v_mul_f32_e32 v105, v107, v106
	v_mul_f32_e32 v104, v105, v104
	v_mul_f32_e32 v104, v131, v104
	v_cvt_pk_bf16_f32 v104, v104, s0
	global_store_short v[110:111], v104, off offset:32
	v_add_u32_e32 v104, v123, v121
	v_or3_b32 v104, v104, v122, v132
	v_ashrrev_i32_e32 v105, 31, v104
	v_lshlrev_b64 v[104:105], 6, v[104:105]
	v_or3_b32 v104, v104, v133, v191
	v_lshl_add_u64 v[104:105], v[104:105], 4, v[114:115]
	v_mul_f32_e32 v106, 0xbfb8aa3b, v100
	v_exp_f32_e32 v106, v106
	s_waitcnt vmcnt(24)
; DI bf16_t f2bf(float x) { return (bf16_t)(cvt_pk(x, 0.f) & 0xffffu); }
; DI float ex2(float x) { return __builtin_amdgcn_exp2f(x); }
; DI size_t vf_off(int item, int dvh, int j) { return ((size_t)((item * 16 + (dvh >> 5)) * 4 + (j >> 4)) * 64 + ((j >> 3) & 1) * 32 + (dvh & 31)) * 8 + (j & 7); }
;     ...
;         const u32x2 ov = *(const u32x2*)((const bf16_t*)(p.ws + OFF_VT1) + vf_off((((pos + 48) >> 6) * 4 + b) * 4 + (col >> 9), col & 511, (pos + 48) & 63));
;         bf16_t* d = (bf16_t*)(p.ws + OFF_YB) + (size_t)row0 * 2048 + col;
; #pragma unroll
;         for (int e = 0; e < 4; ++e) {
;             const unsigned ob = (e & 1) ? (ov[e >> 1] & 0xffff0000u) : (ov[e >> 1] << 16);
;             const float o = __uint_as_float(ob);
;             const float gte = v[e] / (1.f + __expf(-v[e]));
;             d[(size_t)e * 2048] = f2bf(gte * o * s_aux[lrow0 + e]);
; template <int EPI, int K, int LNI = -1>
; DI void ph_gemm(const Params& p, const bf16_t* __restrict__ A, const bf16_t* __restrict__ Bt, int N, float* s_aux) {
;     ...
;             for (int ai = 0; ai < 2; ++ai)
; #pragma unroll
;                 for (int m = 0; m < 4; ++m) {
;                     const int lrow0 = ai * 128 + wr * 64 + m * 16 + fq * 4, row0 = brow + lrow0 + oz;
;                     f32x2 rs[4];
;                     if (EPI == EPI_RESID && LNI >= 0) {
;                         const f32x2* st_ = (const f32x2*)((unsigned char*)p.out + OFFO_STATS) + row0;
; #pragma unroll
;                         for (int e = 0; e < 4; ++e) rs[e] = st_[e];
;                     }
;                     if (EPI == EPI_E5) {
;                         const int idx_ = ((row0 % LT) + 48) & 63; const float lgh = lg_[0][0];
; #pragma unroll
;                         for (int e = 0; e < 4; ++e) rs[e] = (f32x2){ex2(lgh * (float)(idx_ + e + 1)), 0.0625f * ex2(lgh * (float)(63 - idx_ - e))};
;                     }
; #pragma unroll
;                     for (int bj = 0; bj < 2; ++bj)
; #pragma unroll
;                         for (int n = 0; n < 2; ++n) {
;                             float v[4];
; #pragma unroll
;                             for (int e = 0; e < 4; ++e) v[e] = acc[ai][bj][m][n][e];
;                             epi_store<EPI, LNI>(p, row0, bcol + bj * 128 + wc * 32 + n * 16 + fr + oz, lrow0, v, sa, rs, lg_[bj][n], lb_[bj][n]);
	v_mov_b32_e32 v237, v141
	v_add_u32_e32 v228, v192, v175
	v_mul_hi_i32 v229, v228, s68
	v_lshrrev_b32_e32 v230, 31, v229
	v_ashrrev_i32_e32 v229, 12, v229
	v_add_u32_e32 v229, v229, v230
	v_mul_i32_i24_e32 v230, 0xffffdff0, v229
	v_add3_u32 v230, v228, v230, 48
	v_lshrrev_b32_e32 v231, 4, v230
	v_and_b32_e32 v231, 0xfffffc, v231
	v_add_lshl_u32 v232, v231, v229, 8
	v_lshlrev_b32_e32 v229, 2, v230
	v_and_b32_e32 v233, 32, v229
	v_and_b32_e32 v229, 7, v228
	v_bfe_u32 v234, v230, 4, 2
	v_lshlrev_b32_e32 v236, 1, v229
	v_lshl_add_u64 v[238:239], s[20:21], 0, v[236:237]
	v_add_u32_e32 v240, v232, v118
	v_or3_b32 v240, v240, v120, v234
	v_ashrrev_i32_e32 v241, 31, v240
	v_lshlrev_b64 v[240:241], 6, v[240:241]
	v_or3_b32 v240, v240, v233, v119
	v_lshl_add_u64 v[240:241], v[240:241], 4, v[238:239]
	global_load_dwordx2 v[226:227], v[240:241], off
	v_lshlrev_b32_e32 v125, 16, v216
	v_add_f32_e32 v106, 1.0, v106
	s_nop 0
	v_mul_f32_e32 v124, 0xbfb8aa3b, v101
	v_exp_f32_e32 v124, v124
	v_rcp_f32_e32 v107, v106
	s_nop 0
	v_mul_f32_e32 v100, v100, v107
	v_mul_f32_e32 v100, v100, v125
	v_mul_f32_e32 v100, v128, v100
	v_add_f32_e32 v106, 1.0, v124
	v_cvt_pk_bf16_f32 v100, v100, s0
	global_store_short v[112:113], v100, off offset:256
	v_and_b32_e32 v100, 0xffff0000, v216
	v_mul_f32_e32 v107, 0xbfb8aa3b, v102
	v_exp_f32_e32 v107, v107
	v_rcp_f32_e32 v104, v106
	s_nop 0
	v_mul_f32_e32 v101, v101, v104
	v_mul_f32_e32 v100, v101, v100
	v_add_f32_e32 v101, 1.0, v107
	v_mul_f32_e32 v100, v129, v100
	v_cvt_pk_bf16_f32 v100, v100, s0
	global_store_short v[116:117], v100, off offset:256
	v_mul_f32_e32 v106, 0xbfb8aa3b, v103
	v_exp_f32_e32 v106, v106
	v_lshlrev_b32_e32 v100, 16, v217
	v_rcp_f32_e32 v104, v101
	s_nop 0
	v_mul_f32_e32 v101, v102, v104
	v_mul_f32_e32 v100, v101, v100
	v_add_f32_e32 v101, 1.0, v106
	v_mul_f32_e32 v100, v130, v100
	v_cvt_pk_bf16_f32 v100, v100, s0
	global_store_short v[108:109], v100, off offset:256
	v_and_b32_e32 v100, 0xffff0000, v217
	v_rcp_f32_e32 v102, v101
	s_nop 0
	v_mul_f32_e32 v101, v103, v102
	v_mul_f32_e32 v100, v101, v100
	v_mul_f32_e32 v100, v131, v100
	v_cvt_pk_bf16_f32 v100, v100, s0
	global_store_short v[110:111], v100, off offset:256
	v_add_u32_e32 v100, v123, v118
	v_or3_b32 v100, v100, v120, v132
	v_ashrrev_i32_e32 v101, 31, v100
	v_lshlrev_b64 v[100:101], 6, v[100:101]
	v_or3_b32 v100, v100, v133, v119
	v_lshl_add_u64 v[100:101], v[100:101], 4, v[114:115]
	v_mul_f32_e32 v102, 0xbfb8aa3b, v96
	v_exp_f32_e32 v102, v102
	s_waitcnt vmcnt(24)
	v_mov_b32_e32 v237, v141
	v_add_u32_e32 v228, v192, v176
	v_mul_hi_i32 v229, v228, s68
	v_lshrrev_b32_e32 v230, 31, v229
	v_ashrrev_i32_e32 v229, 12, v229
	v_add_u32_e32 v229, v229, v230
	v_mul_i32_i24_e32 v230, 0xffffdff0, v229
	v_add3_u32 v230, v228, v230, 48
	v_lshrrev_b32_e32 v231, 4, v230
	v_and_b32_e32 v231, 0xfffffc, v231
	v_add_lshl_u32 v232, v231, v229, 8
	v_lshlrev_b32_e32 v229, 2, v230
	v_and_b32_e32 v233, 32, v229
	v_and_b32_e32 v229, 7, v228
	v_bfe_u32 v234, v230, 4, 2
	v_lshlrev_b32_e32 v236, 1, v229
	v_add_u32_e32 v229, v232, v193
	v_or3_b32 v238, v229, v194, v234
	v_ashrrev_i32_e32 v239, 31, v238
	v_lshlrev_b64 v[238:239], 6, v[238:239]
	v_lshl_add_u64 v[230:231], s[20:21], 0, v[236:237]
	v_or3_b32 v238, v238, v233, v191
	v_lshl_add_u64 v[238:239], v[238:239], 4, v[230:231]
	global_load_dwordx2 v[216:217], v[238:239], off
	v_lshlrev_b32_e32 v105, 16, v218
	v_add_f32_e32 v102, 1.0, v102
	s_nop 0
	v_mul_f32_e32 v104, 0xbfb8aa3b, v97
	v_exp_f32_e32 v104, v104
	v_rcp_f32_e32 v103, v102
	s_nop 0
	v_mul_f32_e32 v96, v96, v103
	v_mul_f32_e32 v96, v96, v105
	v_mul_f32_e32 v96, v128, v96
	v_add_f32_e32 v102, 1.0, v104
	v_cvt_pk_bf16_f32 v96, v96, s0
	global_store_short v[112:113], v96, off offset:288
	v_and_b32_e32 v96, 0xffff0000, v218
	v_mul_f32_e32 v103, 0xbfb8aa3b, v98
	v_exp_f32_e32 v103, v103
	v_rcp_f32_e32 v100, v102
	s_nop 0
	v_mul_f32_e32 v97, v97, v100
	v_mul_f32_e32 v96, v97, v96
	v_add_f32_e32 v97, 1.0, v103
	v_mul_f32_e32 v96, v129, v96
	v_cvt_pk_bf16_f32 v96, v96, s0
	global_store_short v[116:117], v96, off offset:288
	v_mul_f32_e32 v102, 0xbfb8aa3b, v99
	v_exp_f32_e32 v102, v102
	v_lshlrev_b32_e32 v96, 16, v219
	v_rcp_f32_e32 v100, v97
	s_nop 0
	v_mul_f32_e32 v97, v98, v100
	v_mul_f32_e32 v96, v97, v96
	v_add_f32_e32 v97, 1.0, v102
	v_mul_f32_e32 v96, v130, v96
	v_cvt_pk_bf16_f32 v96, v96, s0
	global_store_short v[108:109], v96, off offset:288
	v_and_b32_e32 v96, 0xffff0000, v219
	v_rcp_f32_e32 v98, v97
	s_nop 0
	v_mul_f32_e32 v97, v99, v98
	v_mul_f32_e32 v96, v97, v96
	v_mul_f32_e32 v96, v131, v96
	v_cvt_pk_bf16_f32 v96, v96, s0
	global_store_short v[110:111], v96, off offset:288
	v_add_u32_e32 v96, v192, v175
	v_mul_hi_i32 v97, v96, s68
	v_lshrrev_b32_e32 v98, 31, v97
	v_ashrrev_i32_e32 v97, 12, v97
	v_add_u32_e32 v97, v97, v98
	v_mul_i32_i24_e32 v98, 0xffffdff0, v97
	v_add3_u32 v98, v96, v98, 48
	v_lshrrev_b32_e32 v99, 4, v98
	v_and_b32_e32 v99, 0xfffffc, v99
	v_add_lshl_u32 v111, v99, v97, 8
	v_lshlrev_b32_e32 v97, 2, v98
	v_and_b32_e32 v110, 32, v97
	v_and_b32_e32 v97, 7, v96
	v_bfe_u32 v112, v98, 4, 2
	v_lshlrev_b32_e32 v140, 1, v97
	v_add_u32_e32 v97, v111, v193
	v_or3_b32 v98, v97, v194, v112
	v_ashrrev_i32_e32 v99, 31, v98
	v_lshlrev_b64 v[98:99], 6, v[98:99]
	v_lshl_add_u64 v[104:105], s[20:21], 0, v[140:141]
	v_or3_b32 v98, v98, v110, v191
	v_lshl_add_u64 v[98:99], v[98:99], 4, v[104:105]
	v_mul_f32_e32 v97, 0xbfb8aa3b, v92
	v_exp_f32_e32 v98, v97
	v_ashrrev_i32_e32 v97, 31, v96
	v_lshlrev_b64 v[96:97], 12, v[96:97]
	v_lshl_add_u64 v[96:97], s[36:37], 0, v[96:97]
	v_add_f32_e32 v98, 1.0, v98
	v_lshl_add_u64 v[106:107], v[96:97], 0, v[146:147]
	ds_read_b128 v[100:103], v195 offset:128
	v_rcp_f32_e32 v97, v98
	s_nop 0
	v_mul_f32_e32 v92, v92, v97
	v_mul_f32_e32 v97, 0xbfb8aa3b, v93
	v_exp_f32_e32 v113, v97
	s_waitcnt vmcnt(24)
; DI bf16_t f2bf(float x) { return (bf16_t)(cvt_pk(x, 0.f) & 0xffffu); }
; DI size_t vf_off(int item, int dvh, int j) { return ((size_t)((item * 16 + (dvh >> 5)) * 4 + (j >> 4)) * 64 + ((j >> 3) & 1) * 32 + (dvh & 31)) * 8 + (j & 7); }
;     ...
;         const u32x2 ov = *(const u32x2*)((const bf16_t*)(p.ws + OFF_VT1) + vf_off((((pos + 48) >> 6) * 4 + b) * 4 + (col >> 9), col & 511, (pos + 48) & 63));
;         bf16_t* d = (bf16_t*)(p.ws + OFF_YB) + (size_t)row0 * 2048 + col;
; #pragma unroll
;         for (int e = 0; e < 4; ++e) {
;             const unsigned ob = (e & 1) ? (ov[e >> 1] & 0xffff0000u) : (ov[e >> 1] << 16);
;             const float o = __uint_as_float(ob);
;             const float gte = v[e] / (1.f + __expf(-v[e]));
;             d[(size_t)e * 2048] = f2bf(gte * o * s_aux[lrow0 + e]);
; template <int EPI, int K, int LNI = -1>
; DI void ph_gemm(const Params& p, const bf16_t* __restrict__ A, const bf16_t* __restrict__ Bt, int N, float* s_aux) {
;     ...
; #pragma unroll
;                     for (int bj = 0; bj < 2; ++bj)
; #pragma unroll
;                         for (int n = 0; n < 2; ++n) {
;                             float v[4];
; #pragma unroll
;                             for (int e = 0; e < 4; ++e) v[e] = acc[ai][bj][m][n][e];
;                             epi_store<EPI, LNI>(p, row0, bcol + bj * 128 + wc * 32 + n * 16 + fr + oz, lrow0, v, sa, rs, lg_[bj][n], lb_[bj][n]);
	v_mov_b32_e32 v237, v141
	v_add_u32_e32 v228, v192, v176
	v_mul_hi_i32 v229, v228, s68
	v_lshrrev_b32_e32 v230, 31, v229
	v_ashrrev_i32_e32 v229, 12, v229
	v_add_u32_e32 v229, v229, v230
	v_mul_i32_i24_e32 v230, 0xffffdff0, v229
	v_add3_u32 v230, v228, v230, 48
	v_lshrrev_b32_e32 v231, 4, v230
	v_and_b32_e32 v231, 0xfffffc, v231
	v_add_lshl_u32 v232, v231, v229, 8
	v_lshlrev_b32_e32 v229, 2, v230
	v_and_b32_e32 v233, 32, v229
	v_and_b32_e32 v229, 7, v228
	v_bfe_u32 v234, v230, 4, 2
	v_lshlrev_b32_e32 v236, 1, v229
	v_lshl_add_u64 v[230:231], s[20:21], 0, v[236:237]
	v_add_u32_e32 v238, v232, v126
	v_or3_b32 v238, v238, v149, v234
	v_ashrrev_i32_e32 v239, 31, v238
	v_lshlrev_b64 v[238:239], 6, v[238:239]
	v_or3_b32 v238, v238, v233, v127
	v_lshl_add_u64 v[238:239], v[238:239], 4, v[230:231]
	global_load_dwordx2 v[218:219], v[238:239], off
	v_lshlrev_b32_e32 v96, 16, v220
	v_add_f32_e32 v113, 1.0, v113
	v_mul_f32_e32 v92, v92, v96
	ds_read_b128 v[96:99], v195 offset:192
	s_waitcnt lgkmcnt(1)
	v_mul_f32_e32 v92, v100, v92
	v_cvt_pk_bf16_f32 v92, v92, s0
	global_store_short v[106:107], v92, off
	v_and_b32_e32 v92, 0xffff0000, v220
	v_rcp_f32_e32 v108, v113
	s_nop 0
	v_mul_f32_e32 v93, v93, v108
	v_mul_f32_e32 v108, 0xbfb8aa3b, v94
	v_exp_f32_e32 v108, v108
	v_mul_f32_e32 v92, v93, v92
	v_mul_f32_e32 v92, v101, v92
	v_cvt_pk_bf16_f32 v113, v92, s0
	v_add_f32_e32 v108, 1.0, v108
	v_add_co_u32_e32 v92, vcc, s3, v106
	s_nop 0
	s_nop 0
	v_addc_co_u32_e32 v93, vcc, 0, v107, vcc
	v_mul_f32_e32 v115, 0xbfb8aa3b, v95
	v_exp_f32_e32 v115, v115
	global_store_short v[92:93], v113, off offset:-4096
	v_lshlrev_b32_e32 v113, 16, v221
	v_rcp_f32_e32 v114, v108
	s_nop 0
	v_mul_f32_e32 v94, v94, v114
	v_add_f32_e32 v108, 1.0, v115
	v_mul_f32_e32 v94, v94, v113
	v_mul_f32_e32 v94, v102, v94
	v_cvt_pk_bf16_f32 v94, v94, s0
	global_store_short v[92:93], v94, off
	v_and_b32_e32 v94, 0xffff0000, v221
	v_rcp_f32_e32 v109, v108
	s_nop 0
	v_mul_f32_e32 v95, v95, v109
	v_mul_f32_e32 v94, v95, v94
	v_mul_f32_e32 v94, v103, v94
	v_cvt_pk_bf16_f32 v108, v94, s0
	v_add_co_u32_e32 v94, vcc, s69, v106
	v_mul_f32_e32 v113, 0xbfb8aa3b, v88
	s_nop 0
	v_addc_co_u32_e32 v95, vcc, 0, v107, vcc
	global_store_short v[94:95], v108, off
	v_add_u32_e32 v108, v111, v126
	v_or3_b32 v108, v108, v149, v112
	v_ashrrev_i32_e32 v109, 31, v108
	v_lshlrev_b64 v[108:109], 6, v[108:109]
	v_or3_b32 v108, v108, v110, v127
	v_lshl_add_u64 v[108:109], v[108:109], 4, v[104:105]
	v_exp_f32_e32 v113, v113
	v_add_co_u32_e32 v114, vcc, s61, v106
	v_add_f32_e32 v113, 1.0, v113
	s_nop 0
	v_addc_co_u32_e32 v115, vcc, 0, v107, vcc
	v_mul_f32_e32 v117, 0xbfb8aa3b, v89
	v_exp_f32_e32 v117, v117
	v_rcp_f32_e32 v116, v113
	s_nop 0
	v_mul_f32_e32 v88, v88, v116
	v_add_f32_e32 v113, 1.0, v117
	s_waitcnt vmcnt(24)
	v_mov_b32_e32 v237, v141
	v_add_u32_e32 v228, v192, v176
	v_mul_hi_i32 v229, v228, s68
	v_lshrrev_b32_e32 v230, 31, v229
	v_ashrrev_i32_e32 v229, 12, v229
	v_add_u32_e32 v229, v229, v230
	v_mul_i32_i24_e32 v230, 0xffffdff0, v229
	v_add3_u32 v230, v228, v230, 48
	v_lshrrev_b32_e32 v231, 4, v230
	v_and_b32_e32 v231, 0xfffffc, v231
	v_add_lshl_u32 v232, v231, v229, 8
	v_lshlrev_b32_e32 v229, 2, v230
	v_and_b32_e32 v233, 32, v229
	v_and_b32_e32 v229, 7, v228
	v_bfe_u32 v234, v230, 4, 2
	v_lshlrev_b32_e32 v236, 1, v229
	v_lshl_add_u64 v[230:231], s[20:21], 0, v[236:237]
	v_add_u32_e32 v238, v232, v121
	v_or3_b32 v238, v238, v122, v234
	v_ashrrev_i32_e32 v239, 31, v238
	v_lshlrev_b64 v[238:239], 6, v[238:239]
	v_or3_b32 v238, v238, v233, v191
	v_lshl_add_u64 v[238:239], v[238:239], 4, v[230:231]
	global_load_dwordx2 v[220:221], v[238:239], off
	v_lshlrev_b32_e32 v123, 16, v222
	v_mul_f32_e32 v88, v88, v123
	v_mul_f32_e32 v88, v100, v88
	v_cvt_pk_bf16_f32 v88, v88, s0
	global_store_short v[106:107], v88, off offset:32
	v_and_b32_e32 v88, 0xffff0000, v222
	v_mul_f32_e32 v116, 0xbfb8aa3b, v90
	v_exp_f32_e32 v116, v116
	v_rcp_f32_e32 v108, v113
	s_nop 0
	v_mul_f32_e32 v89, v89, v108
	v_mul_f32_e32 v88, v89, v88
	v_add_f32_e32 v89, 1.0, v116
	v_mul_f32_e32 v88, v101, v88
	v_cvt_pk_bf16_f32 v88, v88, s0
	global_store_short v[114:115], v88, off offset:32
	v_mul_f32_e32 v113, 0xbfb8aa3b, v91
	v_exp_f32_e32 v113, v113
	v_lshlrev_b32_e32 v88, 16, v223
	v_rcp_f32_e32 v108, v89
	s_nop 0
	v_mul_f32_e32 v89, v90, v108
	v_mul_f32_e32 v88, v89, v88
	v_add_f32_e32 v89, 1.0, v113
	v_mul_f32_e32 v88, v102, v88
	v_cvt_pk_bf16_f32 v88, v88, s0
	global_store_short v[92:93], v88, off offset:32
	v_and_b32_e32 v88, 0xffff0000, v223
	v_rcp_f32_e32 v90, v89
	s_nop 0
	v_mul_f32_e32 v89, v91, v90
	v_mul_f32_e32 v88, v89, v88
	v_mul_f32_e32 v88, v103, v88
	v_cvt_pk_bf16_f32 v88, v88, s0
	global_store_short v[94:95], v88, off offset:32
	v_add_u32_e32 v88, v111, v121
	v_or3_b32 v88, v88, v122, v112
	v_ashrrev_i32_e32 v89, 31, v88
	v_lshlrev_b64 v[88:89], 6, v[88:89]
	v_or3_b32 v88, v88, v110, v191
	v_lshl_add_u64 v[88:89], v[88:89], 4, v[104:105]
	v_mul_f32_e32 v90, 0xbfb8aa3b, v84
	v_exp_f32_e32 v90, v90
	s_waitcnt vmcnt(24)
; DI bf16_t f2bf(float x) { return (bf16_t)(cvt_pk(x, 0.f) & 0xffffu); }
; DI size_t vf_off(int item, int dvh, int j) { return ((size_t)((item * 16 + (dvh >> 5)) * 4 + (j >> 4)) * 64 + ((j >> 3) & 1) * 32 + (dvh & 31)) * 8 + (j & 7); }
;     ...
;     } else if (EPI == EPI_E5B) {
;         const u32x2 ov = *(const u32x2*)((const bf16_t*)(p.ws + OFF_VT1) + vf_off((((pos + 48) >> 6) * 4 + b) * 4 + (col >> 9), col & 511, (pos + 48) & 63));
;         bf16_t* d = (bf16_t*)(p.ws + OFF_YB) + (size_t)row0 * 2048 + col;
; #pragma unroll
;         for (int e = 0; e < 4; ++e) {
;             const unsigned ob = (e & 1) ? (ov[e >> 1] & 0xffff0000u) : (ov[e >> 1] << 16);
;             const float o = __uint_as_float(ob);
;             const float gte = v[e] / (1.f + __expf(-v[e]));
;             d[(size_t)e * 2048] = f2bf(gte * o * s_aux[lrow0 + e]);
;         }
; template <int EPI, int K, int LNI = -1>
; DI void ph_gemm(const Params& p, const bf16_t* __restrict__ A, const bf16_t* __restrict__ Bt, int N, float* s_aux) {
;     ...
; #pragma unroll
;                     for (int bj = 0; bj < 2; ++bj)
; #pragma unroll
;                         for (int n = 0; n < 2; ++n) {
;                             float v[4];
; #pragma unroll
;                             for (int e = 0; e < 4; ++e) v[e] = acc[ai][bj][m][n][e];
;                             epi_store<EPI, LNI>(p, row0, bcol + bj * 128 + wc * 32 + n * 16 + fr + oz, lrow0, v, sa, rs, lg_[bj][n], lb_[bj][n]);
;                         }
	v_mov_b32_e32 v237, v141
	v_add_u32_e32 v228, v192, v176
	v_mul_hi_i32 v229, v228, s68
	v_lshrrev_b32_e32 v230, 31, v229
	v_ashrrev_i32_e32 v229, 12, v229
	v_add_u32_e32 v229, v229, v230
	v_mul_i32_i24_e32 v230, 0xffffdff0, v229
	v_add3_u32 v230, v228, v230, 48
	v_lshrrev_b32_e32 v231, 4, v230
	v_and_b32_e32 v231, 0xfffffc, v231
	v_add_lshl_u32 v232, v231, v229, 8
	v_lshlrev_b32_e32 v229, 2, v230
	v_and_b32_e32 v233, 32, v229
	v_and_b32_e32 v229, 7, v228
	v_bfe_u32 v234, v230, 4, 2
	v_lshlrev_b32_e32 v236, 1, v229
	v_lshl_add_u64 v[230:231], s[20:21], 0, v[236:237]
	v_add_u32_e32 v238, v232, v118
	v_or3_b32 v238, v238, v120, v234
	v_ashrrev_i32_e32 v239, 31, v238
	v_lshlrev_b64 v[238:239], 6, v[238:239]
	v_or3_b32 v238, v238, v233, v119
	v_lshl_add_u64 v[238:239], v[238:239], 4, v[230:231]
	global_load_dwordx2 v[222:223], v[238:239], off
	v_lshlrev_b32_e32 v109, 16, v224
	v_add_f32_e32 v90, 1.0, v90
	s_nop 0
	v_mul_f32_e32 v108, 0xbfb8aa3b, v85
	v_exp_f32_e32 v108, v108
	v_rcp_f32_e32 v91, v90
	s_nop 0
	v_mul_f32_e32 v84, v84, v91
	v_mul_f32_e32 v84, v84, v109
	v_mul_f32_e32 v84, v100, v84
	v_add_f32_e32 v90, 1.0, v108
	v_cvt_pk_bf16_f32 v84, v84, s0
	global_store_short v[106:107], v84, off offset:256
	v_and_b32_e32 v84, 0xffff0000, v224
	v_mul_f32_e32 v91, 0xbfb8aa3b, v86
	v_exp_f32_e32 v91, v91
	v_rcp_f32_e32 v88, v90
	s_nop 0
	v_mul_f32_e32 v85, v85, v88
	v_mul_f32_e32 v84, v85, v84
	v_add_f32_e32 v85, 1.0, v91
	v_mul_f32_e32 v84, v101, v84
	v_cvt_pk_bf16_f32 v84, v84, s0
	global_store_short v[114:115], v84, off offset:256
	v_mul_f32_e32 v90, 0xbfb8aa3b, v87
	v_exp_f32_e32 v90, v90
	v_lshlrev_b32_e32 v84, 16, v225
	v_rcp_f32_e32 v88, v85
	s_nop 0
	v_mul_f32_e32 v85, v86, v88
	v_mul_f32_e32 v84, v85, v84
	v_add_f32_e32 v85, 1.0, v90
	v_mul_f32_e32 v84, v102, v84
	v_cvt_pk_bf16_f32 v84, v84, s0
	global_store_short v[92:93], v84, off offset:256
	v_and_b32_e32 v84, 0xffff0000, v225
	v_rcp_f32_e32 v86, v85
	s_nop 0
	v_mul_f32_e32 v85, v87, v86
	v_mul_f32_e32 v84, v85, v84
	v_mul_f32_e32 v84, v103, v84
	v_cvt_pk_bf16_f32 v84, v84, s0
	global_store_short v[94:95], v84, off offset:256
	v_add_u32_e32 v84, v111, v118
	v_or3_b32 v84, v84, v120, v112
	v_ashrrev_i32_e32 v85, 31, v84
	v_lshlrev_b64 v[84:85], 6, v[84:85]
	v_or3_b32 v84, v84, v110, v119
	v_lshl_add_u64 v[84:85], v[84:85], 4, v[104:105]
	v_mul_f32_e32 v86, 0xbfb8aa3b, v80
	v_exp_f32_e32 v86, v86
	s_waitcnt vmcnt(24)
	v_mov_b32_e32 v237, v141
	v_add_u32_e32 v228, v192, v177
	v_mul_hi_i32 v229, v228, s68
	v_lshrrev_b32_e32 v230, 31, v229
	v_ashrrev_i32_e32 v229, 12, v229
	v_add_u32_e32 v229, v229, v230
	v_mul_i32_i24_e32 v230, 0xffffdff0, v229
	v_add3_u32 v230, v228, v230, 48
	v_lshrrev_b32_e32 v231, 4, v230
	v_and_b32_e32 v231, 0xfffffc, v231
	v_add_lshl_u32 v232, v231, v229, 8
	v_lshlrev_b32_e32 v229, 2, v230
	v_and_b32_e32 v233, 32, v229
	v_and_b32_e32 v229, 7, v228
	v_bfe_u32 v234, v230, 4, 2
	v_lshlrev_b32_e32 v236, 1, v229
	v_add_u32_e32 v229, v232, v193
	v_or3_b32 v230, v229, v194, v234
	v_ashrrev_i32_e32 v231, 31, v230
	v_lshlrev_b64 v[230:231], 6, v[230:231]
	v_lshl_add_u64 v[238:239], s[20:21], 0, v[236:237]
	v_or3_b32 v230, v230, v233, v191
	v_lshl_add_u64 v[230:231], v[230:231], 4, v[238:239]
	global_load_dwordx2 v[224:225], v[230:231], off
	v_lshlrev_b32_e32 v89, 16, v226
	v_add_f32_e32 v86, 1.0, v86
	s_nop 0
	v_mul_f32_e32 v88, 0xbfb8aa3b, v81
	v_exp_f32_e32 v88, v88
	v_rcp_f32_e32 v87, v86
	s_nop 0
	v_mul_f32_e32 v80, v80, v87
	v_mul_f32_e32 v80, v80, v89
	v_mul_f32_e32 v80, v100, v80
	v_add_f32_e32 v86, 1.0, v88
	v_cvt_pk_bf16_f32 v80, v80, s0
	global_store_short v[106:107], v80, off offset:288
	v_and_b32_e32 v80, 0xffff0000, v226
	v_mul_f32_e32 v87, 0xbfb8aa3b, v82
	v_exp_f32_e32 v87, v87
	v_rcp_f32_e32 v84, v86
	s_nop 0
	v_mul_f32_e32 v81, v81, v84
	v_mul_f32_e32 v80, v81, v80
	v_add_f32_e32 v81, 1.0, v87
	v_mul_f32_e32 v80, v101, v80
	v_cvt_pk_bf16_f32 v80, v80, s0
	global_store_short v[114:115], v80, off offset:288
	v_mul_f32_e32 v86, 0xbfb8aa3b, v83
	v_exp_f32_e32 v86, v86
	v_lshlrev_b32_e32 v80, 16, v227
	v_rcp_f32_e32 v84, v81
	s_nop 0
	v_mul_f32_e32 v81, v82, v84
	v_mul_f32_e32 v80, v81, v80
	v_add_f32_e32 v81, 1.0, v86
	v_mul_f32_e32 v80, v102, v80
	v_cvt_pk_bf16_f32 v80, v80, s0
	global_store_short v[92:93], v80, off offset:288
	v_and_b32_e32 v80, 0xffff0000, v227
	v_rcp_f32_e32 v82, v81
	s_nop 0
	v_mul_f32_e32 v81, v83, v82
	v_mul_f32_e32 v80, v81, v80
	v_mul_f32_e32 v80, v103, v80
	v_cvt_pk_bf16_f32 v80, v80, s0
	global_store_short v[94:95], v80, off offset:288
	v_add_u32_e32 v80, v192, v176
	v_mul_hi_i32 v81, v80, s68
	v_lshrrev_b32_e32 v82, 31, v81
	v_ashrrev_i32_e32 v81, 12, v81
	v_add_u32_e32 v81, v81, v82
	v_mul_i32_i24_e32 v82, 0xffffdff0, v81
	v_add3_u32 v82, v80, v82, 48
	v_lshrrev_b32_e32 v83, 4, v82
	v_and_b32_e32 v83, 0xfffffc, v83
	v_add_lshl_u32 v88, v83, v81, 8
	v_lshlrev_b32_e32 v81, 2, v82
	v_and_b32_e32 v90, 32, v81
	v_and_b32_e32 v81, 7, v80
	v_bfe_u32 v89, v82, 4, 2
	v_lshlrev_b32_e32 v140, 1, v81
	v_add_u32_e32 v81, v88, v193
	v_or3_b32 v84, v81, v194, v89
	v_ashrrev_i32_e32 v85, 31, v84
	v_lshlrev_b64 v[84:85], 6, v[84:85]
	v_lshl_add_u64 v[82:83], s[20:21], 0, v[140:141]
	v_or3_b32 v84, v84, v90, v191
	v_lshl_add_u64 v[84:85], v[84:85], 4, v[82:83]
	v_mul_f32_e32 v81, 0xbfb8aa3b, v76
	v_exp_f32_e32 v86, v81
	v_ashrrev_i32_e32 v81, 31, v80
	v_lshlrev_b64 v[80:81], 12, v[80:81]
	v_lshl_add_u64 v[80:81], s[36:37], 0, v[80:81]
	v_add_f32_e32 v86, 1.0, v86
	v_lshl_add_u64 v[80:81], v[80:81], 0, v[146:147]
	v_mul_f32_e32 v91, 0xbfb8aa3b, v77
	v_exp_f32_e32 v91, v91
	v_rcp_f32_e32 v87, v86
	s_nop 0
	v_mul_f32_e32 v76, v76, v87
	v_add_f32_e32 v86, 1.0, v91
	s_waitcnt vmcnt(24)
; DI bf16_t f2bf(float x) { return (bf16_t)(cvt_pk(x, 0.f) & 0xffffu); }
; DI size_t vf_off(int item, int dvh, int j) { return ((size_t)((item * 16 + (dvh >> 5)) * 4 + (j >> 4)) * 64 + ((j >> 3) & 1) * 32 + (dvh & 31)) * 8 + (j & 7); }
;     ...
;     } else if (EPI == EPI_E5B) {
;         const u32x2 ov = *(const u32x2*)((const bf16_t*)(p.ws + OFF_VT1) + vf_off((((pos + 48) >> 6) * 4 + b) * 4 + (col >> 9), col & 511, (pos + 48) & 63));
;         bf16_t* d = (bf16_t*)(p.ws + OFF_YB) + (size_t)row0 * 2048 + col;
; #pragma unroll
;         for (int e = 0; e < 4; ++e) {
;             const unsigned ob = (e & 1) ? (ov[e >> 1] & 0xffff0000u) : (ov[e >> 1] << 16);
;             const float o = __uint_as_float(ob);
;             const float gte = v[e] / (1.f + __expf(-v[e]));
;             d[(size_t)e * 2048] = f2bf(gte * o * s_aux[lrow0 + e]);
;         }
; template <int EPI, int K, int LNI = -1>
; DI void ph_gemm(const Params& p, const bf16_t* __restrict__ A, const bf16_t* __restrict__ Bt, int N, float* s_aux) {
;     ...
; #pragma unroll
;                     for (int bj = 0; bj < 2; ++bj)
; #pragma unroll
;                         for (int n = 0; n < 2; ++n) {
;                             float v[4];
; #pragma unroll
;                             for (int e = 0; e < 4; ++e) v[e] = acc[ai][bj][m][n][e];
;                             epi_store<EPI, LNI>(p, row0, bcol + bj * 128 + wc * 32 + n * 16 + fr + oz, lrow0, v, sa, rs, lg_[bj][n], lb_[bj][n]);
;                         }
	v_mov_b32_e32 v237, v141
	v_add_u32_e32 v228, v192, v177
	v_mul_hi_i32 v229, v228, s68
	v_lshrrev_b32_e32 v230, 31, v229
	v_ashrrev_i32_e32 v229, 12, v229
	v_add_u32_e32 v229, v229, v230
	v_mul_i32_i24_e32 v230, 0xffffdff0, v229
	v_add3_u32 v230, v228, v230, 48
	v_lshrrev_b32_e32 v231, 4, v230
	v_and_b32_e32 v231, 0xfffffc, v231
	v_add_lshl_u32 v232, v231, v229, 8
	v_lshlrev_b32_e32 v229, 2, v230
	v_and_b32_e32 v233, 32, v229
	v_and_b32_e32 v229, 7, v228
	v_bfe_u32 v234, v230, 4, 2
	v_lshlrev_b32_e32 v236, 1, v229
	v_lshl_add_u64 v[238:239], s[20:21], 0, v[236:237]
	v_add_u32_e32 v240, v232, v126
	v_or3_b32 v240, v240, v149, v234
	v_ashrrev_i32_e32 v241, 31, v240
	v_lshlrev_b64 v[240:241], 6, v[240:241]
	v_or3_b32 v240, v240, v233, v127
	v_lshl_add_u64 v[240:241], v[240:241], 4, v[238:239]
	global_load_dwordx2 v[226:227], v[240:241], off
	v_lshlrev_b32_e32 v92, 16, v216
	v_mul_f32_e32 v76, v76, v92
	s_waitcnt lgkmcnt(0)
	v_mul_f32_e32 v76, v96, v76
	v_cvt_pk_bf16_f32 v76, v76, s0
	global_store_short v[80:81], v76, off
	v_and_b32_e32 v76, 0xffff0000, v216
	v_rcp_f32_e32 v84, v86
	s_nop 0
	v_mul_f32_e32 v77, v77, v84
	v_mul_f32_e32 v84, 0xbfb8aa3b, v78
	v_exp_f32_e32 v84, v84
	v_mul_f32_e32 v76, v77, v76
	v_mul_f32_e32 v76, v97, v76
	v_cvt_pk_bf16_f32 v86, v76, s0
	v_add_f32_e32 v84, 1.0, v84
	v_add_co_u32_e32 v76, vcc, s3, v80
	s_nop 0
	s_nop 0
	v_addc_co_u32_e32 v77, vcc, 0, v81, vcc
	v_mul_f32_e32 v91, 0xbfb8aa3b, v79
	v_exp_f32_e32 v91, v91
	global_store_short v[76:77], v86, off offset:-4096
	v_lshlrev_b32_e32 v86, 16, v217
	v_rcp_f32_e32 v87, v84
	s_nop 0
	v_mul_f32_e32 v78, v78, v87
	v_add_f32_e32 v84, 1.0, v91
	v_mul_f32_e32 v78, v78, v86
	v_mul_f32_e32 v78, v98, v78
	v_cvt_pk_bf16_f32 v78, v78, s0
	global_store_short v[76:77], v78, off
	v_and_b32_e32 v78, 0xffff0000, v217
	v_rcp_f32_e32 v85, v84
	s_nop 0
	v_mul_f32_e32 v79, v79, v85
	v_mul_f32_e32 v78, v79, v78
	v_mul_f32_e32 v78, v99, v78
	v_cvt_pk_bf16_f32 v84, v78, s0
	v_add_co_u32_e32 v78, vcc, s69, v80
	s_nop 1
	v_addc_co_u32_e32 v79, vcc, 0, v81, vcc
	global_store_short v[78:79], v84, off
	v_add_u32_e32 v84, v88, v126
	v_or3_b32 v84, v84, v149, v89
	v_ashrrev_i32_e32 v85, 31, v84
	v_lshlrev_b64 v[84:85], 6, v[84:85]
	v_or3_b32 v84, v84, v90, v127
	v_lshl_add_u64 v[84:85], v[84:85], 4, v[82:83]
	v_mul_f32_e32 v84, 0xbfb8aa3b, v72
	v_exp_f32_e32 v84, v84
	s_waitcnt vmcnt(24)
	v_mov_b32_e32 v237, v141
	v_add_u32_e32 v228, v192, v177
	v_mul_hi_i32 v229, v228, s68
	v_lshrrev_b32_e32 v230, 31, v229
	v_ashrrev_i32_e32 v229, 12, v229
	v_add_u32_e32 v229, v229, v230
	v_mul_i32_i24_e32 v230, 0xffffdff0, v229
	v_add3_u32 v230, v228, v230, 48
	v_lshrrev_b32_e32 v231, 4, v230
	v_and_b32_e32 v231, 0xfffffc, v231
	v_add_lshl_u32 v232, v231, v229, 8
	v_lshlrev_b32_e32 v229, 2, v230
	v_and_b32_e32 v233, 32, v229
	v_and_b32_e32 v229, 7, v228
	v_bfe_u32 v234, v230, 4, 2
	v_lshlrev_b32_e32 v236, 1, v229
	v_lshl_add_u64 v[238:239], s[20:21], 0, v[236:237]
	v_add_u32_e32 v240, v232, v121
	v_or3_b32 v240, v240, v122, v234
	v_ashrrev_i32_e32 v241, 31, v240
	v_lshlrev_b64 v[240:241], 6, v[240:241]
	v_or3_b32 v240, v240, v233, v191
	v_lshl_add_u64 v[240:241], v[240:241], 4, v[238:239]
	global_load_dwordx2 v[216:217], v[240:241], off
	v_lshlrev_b32_e32 v94, 16, v218
	v_add_f32_e32 v91, 1.0, v84
	v_add_co_u32_e32 v84, vcc, s61, v80
	s_nop 0
	s_nop 0
	v_addc_co_u32_e32 v85, vcc, 0, v81, vcc
	v_mul_f32_e32 v93, 0xbfb8aa3b, v73
	v_exp_f32_e32 v93, v93
	v_rcp_f32_e32 v92, v91
	s_nop 0
	v_mul_f32_e32 v72, v72, v92
	v_mul_f32_e32 v72, v72, v94
	v_mul_f32_e32 v72, v96, v72
	v_add_f32_e32 v91, 1.0, v93
	v_cvt_pk_bf16_f32 v72, v72, s0
	global_store_short v[80:81], v72, off offset:32
	v_and_b32_e32 v72, 0xffff0000, v218
	v_mul_f32_e32 v92, 0xbfb8aa3b, v74
	v_exp_f32_e32 v92, v92
	v_rcp_f32_e32 v86, v91
	s_nop 0
	v_mul_f32_e32 v73, v73, v86
	v_mul_f32_e32 v72, v73, v72
	v_add_f32_e32 v73, 1.0, v92
	v_mul_f32_e32 v72, v97, v72
	v_cvt_pk_bf16_f32 v72, v72, s0
	global_store_short v[84:85], v72, off offset:32
	v_mul_f32_e32 v91, 0xbfb8aa3b, v75
	v_exp_f32_e32 v91, v91
	v_lshlrev_b32_e32 v72, 16, v219
	v_rcp_f32_e32 v86, v73
	s_nop 0
	v_mul_f32_e32 v73, v74, v86
	v_mul_f32_e32 v72, v73, v72
	v_add_f32_e32 v73, 1.0, v91
	v_mul_f32_e32 v72, v98, v72
	v_cvt_pk_bf16_f32 v72, v72, s0
	global_store_short v[76:77], v72, off offset:32
	v_and_b32_e32 v72, 0xffff0000, v219
	v_rcp_f32_e32 v74, v73
	s_nop 0
	v_mul_f32_e32 v73, v75, v74
	v_mul_f32_e32 v72, v73, v72
	v_mul_f32_e32 v72, v99, v72
	v_cvt_pk_bf16_f32 v72, v72, s0
	global_store_short v[78:79], v72, off offset:32
	v_add_u32_e32 v72, v88, v121
	v_or3_b32 v72, v72, v122, v89
	v_ashrrev_i32_e32 v73, 31, v72
	v_lshlrev_b64 v[72:73], 6, v[72:73]
	v_or3_b32 v72, v72, v90, v191
	v_lshl_add_u64 v[72:73], v[72:73], 4, v[82:83]
	v_mul_f32_e32 v74, 0xbfb8aa3b, v68
	v_exp_f32_e32 v74, v74
	s_waitcnt vmcnt(24)
; DI bf16_t f2bf(float x) { return (bf16_t)(cvt_pk(x, 0.f) & 0xffffu); }
; DI size_t vf_off(int item, int dvh, int j) { return ((size_t)((item * 16 + (dvh >> 5)) * 4 + (j >> 4)) * 64 + ((j >> 3) & 1) * 32 + (dvh & 31)) * 8 + (j & 7); }
;     ...
;     } else if (EPI == EPI_E5B) {
;         const u32x2 ov = *(const u32x2*)((const bf16_t*)(p.ws + OFF_VT1) + vf_off((((pos + 48) >> 6) * 4 + b) * 4 + (col >> 9), col & 511, (pos + 48) & 63));
;         bf16_t* d = (bf16_t*)(p.ws + OFF_YB) + (size_t)row0 * 2048 + col;
; #pragma unroll
;         for (int e = 0; e < 4; ++e) {
;             const unsigned ob = (e & 1) ? (ov[e >> 1] & 0xffff0000u) : (ov[e >> 1] << 16);
;             const float o = __uint_as_float(ob);
;             const float gte = v[e] / (1.f + __expf(-v[e]));
;             d[(size_t)e * 2048] = f2bf(gte * o * s_aux[lrow0 + e]);
;         }
; template <int EPI, int K, int LNI = -1>
; DI void ph_gemm(const Params& p, const bf16_t* __restrict__ A, const bf16_t* __restrict__ Bt, int N, float* s_aux) {
;     ...
; #pragma unroll
;                     for (int bj = 0; bj < 2; ++bj)
; #pragma unroll
;                         for (int n = 0; n < 2; ++n) {
;                             float v[4];
; #pragma unroll
;                             for (int e = 0; e < 4; ++e) v[e] = acc[ai][bj][m][n][e];
;                             epi_store<EPI, LNI>(p, row0, bcol + bj * 128 + wc * 32 + n * 16 + fr + oz, lrow0, v, sa, rs, lg_[bj][n], lb_[bj][n]);
;                         }
	v_mov_b32_e32 v237, v141
	v_add_u32_e32 v228, v192, v177
	v_mul_hi_i32 v229, v228, s68
	v_lshrrev_b32_e32 v230, 31, v229
	v_ashrrev_i32_e32 v229, 12, v229
	v_add_u32_e32 v229, v229, v230
	v_mul_i32_i24_e32 v230, 0xffffdff0, v229
	v_add3_u32 v230, v228, v230, 48
	v_lshrrev_b32_e32 v231, 4, v230
	v_and_b32_e32 v231, 0xfffffc, v231
	v_add_lshl_u32 v232, v231, v229, 8
	v_lshlrev_b32_e32 v229, 2, v230
	v_and_b32_e32 v233, 32, v229
	v_and_b32_e32 v229, 7, v228
	v_bfe_u32 v234, v230, 4, 2
	v_lshlrev_b32_e32 v236, 1, v229
	v_lshl_add_u64 v[238:239], s[20:21], 0, v[236:237]
	v_add_u32_e32 v240, v232, v118
	v_or3_b32 v240, v240, v120, v234
	v_ashrrev_i32_e32 v241, 31, v240
	v_lshlrev_b64 v[240:241], 6, v[240:241]
	v_or3_b32 v240, v240, v233, v119
	v_lshl_add_u64 v[240:241], v[240:241], 4, v[238:239]
	global_load_dwordx2 v[218:219], v[240:241], off
	v_lshlrev_b32_e32 v87, 16, v220
	v_add_f32_e32 v74, 1.0, v74
	s_nop 0
	v_mul_f32_e32 v86, 0xbfb8aa3b, v69
	v_exp_f32_e32 v86, v86
	v_rcp_f32_e32 v75, v74
	s_nop 0
	v_mul_f32_e32 v68, v68, v75
	v_mul_f32_e32 v68, v68, v87
	v_mul_f32_e32 v68, v96, v68
	v_add_f32_e32 v74, 1.0, v86
	v_cvt_pk_bf16_f32 v68, v68, s0
	global_store_short v[80:81], v68, off offset:256
	v_and_b32_e32 v68, 0xffff0000, v220
	v_mul_f32_e32 v75, 0xbfb8aa3b, v70
	v_exp_f32_e32 v75, v75
	v_rcp_f32_e32 v72, v74
	s_nop 0
	v_mul_f32_e32 v69, v69, v72
	v_mul_f32_e32 v68, v69, v68
	v_add_f32_e32 v69, 1.0, v75
	v_mul_f32_e32 v68, v97, v68
	v_cvt_pk_bf16_f32 v68, v68, s0
	global_store_short v[84:85], v68, off offset:256
	v_mul_f32_e32 v74, 0xbfb8aa3b, v71
	v_exp_f32_e32 v74, v74
	v_lshlrev_b32_e32 v68, 16, v221
	v_rcp_f32_e32 v72, v69
	s_nop 0
	v_mul_f32_e32 v69, v70, v72
	v_mul_f32_e32 v68, v69, v68
	v_add_f32_e32 v69, 1.0, v74
	v_mul_f32_e32 v68, v98, v68
	v_cvt_pk_bf16_f32 v68, v68, s0
	global_store_short v[76:77], v68, off offset:256
	v_and_b32_e32 v68, 0xffff0000, v221
	v_rcp_f32_e32 v70, v69
	s_nop 0
	v_mul_f32_e32 v69, v71, v70
	v_mul_f32_e32 v68, v69, v68
	v_mul_f32_e32 v68, v99, v68
	v_cvt_pk_bf16_f32 v68, v68, s0
	global_store_short v[78:79], v68, off offset:256
	v_add_u32_e32 v68, v88, v118
	v_or3_b32 v68, v68, v120, v89
	v_ashrrev_i32_e32 v69, 31, v68
	v_lshlrev_b64 v[68:69], 6, v[68:69]
	v_or3_b32 v68, v68, v90, v119
	v_lshl_add_u64 v[68:69], v[68:69], 4, v[82:83]
	v_mul_f32_e32 v70, 0xbfb8aa3b, v64
	v_exp_f32_e32 v70, v70
	s_waitcnt vmcnt(24)
	v_mov_b32_e32 v237, v141
	v_add_u32_e32 v228, v192, v178
	v_mul_hi_i32 v229, v228, s68
	v_lshrrev_b32_e32 v230, 31, v229
	v_ashrrev_i32_e32 v229, 12, v229
	v_add_u32_e32 v229, v229, v230
	v_mul_i32_i24_e32 v230, 0xffffdff0, v229
	v_add3_u32 v230, v228, v230, 48
	v_lshrrev_b32_e32 v231, 4, v230
	v_and_b32_e32 v231, 0xfffffc, v231
	v_add_lshl_u32 v232, v231, v229, 8
	v_lshlrev_b32_e32 v229, 2, v230
	v_and_b32_e32 v233, 32, v229
	v_and_b32_e32 v229, 7, v228
	v_bfe_u32 v234, v230, 4, 2
	v_lshlrev_b32_e32 v236, 1, v229
	v_add_u32_e32 v229, v232, v193
	v_or3_b32 v238, v229, v194, v234
	v_ashrrev_i32_e32 v239, 31, v238
	v_lshlrev_b64 v[238:239], 6, v[238:239]
	v_lshl_add_u64 v[230:231], s[20:21], 0, v[236:237]
	v_or3_b32 v238, v238, v233, v191
	v_lshl_add_u64 v[238:239], v[238:239], 4, v[230:231]
	global_load_dwordx2 v[220:221], v[238:239], off
	v_lshlrev_b32_e32 v73, 16, v222
	v_add_f32_e32 v70, 1.0, v70
	s_nop 0
	v_mul_f32_e32 v72, 0xbfb8aa3b, v65
	v_exp_f32_e32 v72, v72
	v_rcp_f32_e32 v71, v70
	s_nop 0
	v_mul_f32_e32 v64, v64, v71
	v_mul_f32_e32 v64, v64, v73
	v_mul_f32_e32 v64, v96, v64
	v_add_f32_e32 v70, 1.0, v72
	v_cvt_pk_bf16_f32 v64, v64, s0
	global_store_short v[80:81], v64, off offset:288
	v_and_b32_e32 v64, 0xffff0000, v222
	v_mul_f32_e32 v71, 0xbfb8aa3b, v66
	v_exp_f32_e32 v71, v71
	v_rcp_f32_e32 v68, v70
	s_nop 0
	v_mul_f32_e32 v65, v65, v68
	v_mul_f32_e32 v64, v65, v64
	v_add_f32_e32 v65, 1.0, v71
	v_mul_f32_e32 v64, v97, v64
	v_cvt_pk_bf16_f32 v64, v64, s0
	global_store_short v[84:85], v64, off offset:288
	v_mul_f32_e32 v70, 0xbfb8aa3b, v67
	v_exp_f32_e32 v70, v70
	v_lshlrev_b32_e32 v64, 16, v223
	v_rcp_f32_e32 v68, v65
	s_nop 0
	v_mul_f32_e32 v65, v66, v68
	v_mul_f32_e32 v64, v65, v64
	v_add_f32_e32 v65, 1.0, v70
	v_mul_f32_e32 v64, v98, v64
	v_cvt_pk_bf16_f32 v64, v64, s0
	global_store_short v[76:77], v64, off offset:288
	v_and_b32_e32 v64, 0xffff0000, v223
	v_rcp_f32_e32 v66, v65
	s_nop 0
	v_mul_f32_e32 v65, v67, v66
	v_mul_f32_e32 v64, v65, v64
	v_mul_f32_e32 v64, v99, v64
	v_cvt_pk_bf16_f32 v64, v64, s0
	global_store_short v[78:79], v64, off offset:288
	v_add_u32_e32 v64, v192, v177
	v_mul_hi_i32 v65, v64, s68
	v_lshrrev_b32_e32 v66, 31, v65
	v_ashrrev_i32_e32 v65, 12, v65
	v_add_u32_e32 v65, v65, v66
	v_mul_i32_i24_e32 v66, 0xffffdff0, v65
	v_add3_u32 v66, v64, v66, 48
	v_lshrrev_b32_e32 v67, 4, v66
	v_and_b32_e32 v67, 0xfffffc, v67
	v_add_lshl_u32 v79, v67, v65, 8
	v_lshlrev_b32_e32 v65, 2, v66
	v_and_b32_e32 v78, 32, v65
	v_and_b32_e32 v65, 7, v64
	v_bfe_u32 v80, v66, 4, 2
	v_lshlrev_b32_e32 v140, 1, v65
	v_add_u32_e32 v65, v79, v193
	v_or3_b32 v66, v65, v194, v80
	v_ashrrev_i32_e32 v67, 31, v66
	v_lshlrev_b64 v[66:67], 6, v[66:67]
	v_lshl_add_u64 v[72:73], s[20:21], 0, v[140:141]
	v_or3_b32 v66, v66, v78, v191
	v_lshl_add_u64 v[66:67], v[66:67], 4, v[72:73]
	v_mul_f32_e32 v65, 0xbfb8aa3b, v60
	v_exp_f32_e32 v66, v65
	v_ashrrev_i32_e32 v65, 31, v64
	v_lshlrev_b64 v[64:65], 12, v[64:65]
	v_lshl_add_u64 v[64:65], s[36:37], 0, v[64:65]
	v_add_f32_e32 v66, 1.0, v66
	v_lshl_add_u64 v[74:75], v[64:65], 0, v[146:147]
	ds_read_b128 v[68:71], v195 offset:512
	v_rcp_f32_e32 v65, v66
	s_nop 0
	v_mul_f32_e32 v60, v60, v65
	v_mul_f32_e32 v65, 0xbfb8aa3b, v61
	v_exp_f32_e32 v81, v65
	s_waitcnt vmcnt(24)
; DI bf16_t f2bf(float x) { return (bf16_t)(cvt_pk(x, 0.f) & 0xffffu); }
; DI size_t vf_off(int item, int dvh, int j) { return ((size_t)((item * 16 + (dvh >> 5)) * 4 + (j >> 4)) * 64 + ((j >> 3) & 1) * 32 + (dvh & 31)) * 8 + (j & 7); }
;     ...
;     } else if (EPI == EPI_E5B) {
;         const u32x2 ov = *(const u32x2*)((const bf16_t*)(p.ws + OFF_VT1) + vf_off((((pos + 48) >> 6) * 4 + b) * 4 + (col >> 9), col & 511, (pos + 48) & 63));
;         bf16_t* d = (bf16_t*)(p.ws + OFF_YB) + (size_t)row0 * 2048 + col;
; #pragma unroll
;         for (int e = 0; e < 4; ++e) {
;             const unsigned ob = (e & 1) ? (ov[e >> 1] & 0xffff0000u) : (ov[e >> 1] << 16);
;             const float o = __uint_as_float(ob);
;             const float gte = v[e] / (1.f + __expf(-v[e]));
;             d[(size_t)e * 2048] = f2bf(gte * o * s_aux[lrow0 + e]);
;         }
; template <int EPI, int K, int LNI = -1>
; DI void ph_gemm(const Params& p, const bf16_t* __restrict__ A, const bf16_t* __restrict__ Bt, int N, float* s_aux) {
;     ...
; #pragma unroll
;                     for (int bj = 0; bj < 2; ++bj)
; #pragma unroll
;                         for (int n = 0; n < 2; ++n) {
;                             float v[4];
; #pragma unroll
;                             for (int e = 0; e < 4; ++e) v[e] = acc[ai][bj][m][n][e];
;                             epi_store<EPI, LNI>(p, row0, bcol + bj * 128 + wc * 32 + n * 16 + fr + oz, lrow0, v, sa, rs, lg_[bj][n], lb_[bj][n]);
;                         }
	v_mov_b32_e32 v237, v141
	v_add_u32_e32 v228, v192, v178
	v_mul_hi_i32 v229, v228, s68
	v_lshrrev_b32_e32 v230, 31, v229
	v_ashrrev_i32_e32 v229, 12, v229
	v_add_u32_e32 v229, v229, v230
	v_mul_i32_i24_e32 v230, 0xffffdff0, v229
	v_add3_u32 v230, v228, v230, 48
	v_lshrrev_b32_e32 v231, 4, v230
	v_and_b32_e32 v231, 0xfffffc, v231
	v_add_lshl_u32 v232, v231, v229, 8
	v_lshlrev_b32_e32 v229, 2, v230
	v_and_b32_e32 v233, 32, v229
	v_and_b32_e32 v229, 7, v228
	v_bfe_u32 v234, v230, 4, 2
	v_lshlrev_b32_e32 v236, 1, v229
	v_lshl_add_u64 v[230:231], s[20:21], 0, v[236:237]
	v_add_u32_e32 v238, v232, v126
	v_or3_b32 v238, v238, v149, v234
	v_ashrrev_i32_e32 v239, 31, v238
	v_lshlrev_b64 v[238:239], 6, v[238:239]
	v_or3_b32 v238, v238, v233, v127
	v_lshl_add_u64 v[238:239], v[238:239], 4, v[230:231]
	global_load_dwordx2 v[222:223], v[238:239], off
	v_lshlrev_b32_e32 v64, 16, v224
	v_add_f32_e32 v81, 1.0, v81
	v_mul_f32_e32 v60, v60, v64
	ds_read_b128 v[64:67], v195 offset:576
	s_waitcnt lgkmcnt(1)
	v_mul_f32_e32 v60, v68, v60
	v_cvt_pk_bf16_f32 v60, v60, s0
	global_store_short v[74:75], v60, off
	v_and_b32_e32 v60, 0xffff0000, v224
	v_rcp_f32_e32 v76, v81
	s_nop 0
	v_mul_f32_e32 v61, v61, v76
	v_mul_f32_e32 v76, 0xbfb8aa3b, v62
	v_exp_f32_e32 v76, v76
	v_mul_f32_e32 v60, v61, v60
	v_mul_f32_e32 v60, v69, v60
	v_cvt_pk_bf16_f32 v81, v60, s0
	v_add_f32_e32 v76, 1.0, v76
	v_add_co_u32_e32 v60, vcc, s3, v74
	s_nop 0
	s_nop 0
	v_addc_co_u32_e32 v61, vcc, 0, v75, vcc
	v_mul_f32_e32 v83, 0xbfb8aa3b, v63
	v_exp_f32_e32 v83, v83
	global_store_short v[60:61], v81, off offset:-4096
	v_lshlrev_b32_e32 v81, 16, v225
	v_rcp_f32_e32 v82, v76
	s_nop 0
	v_mul_f32_e32 v62, v62, v82
	v_add_f32_e32 v76, 1.0, v83
	v_mul_f32_e32 v62, v62, v81
	v_mul_f32_e32 v62, v70, v62
	v_cvt_pk_bf16_f32 v62, v62, s0
	global_store_short v[60:61], v62, off
	v_and_b32_e32 v62, 0xffff0000, v225
	v_rcp_f32_e32 v77, v76
	s_nop 0
	v_mul_f32_e32 v63, v63, v77
	v_mul_f32_e32 v62, v63, v62
	v_mul_f32_e32 v62, v71, v62
	v_cvt_pk_bf16_f32 v76, v62, s0
	v_add_co_u32_e32 v62, vcc, s69, v74
	v_mul_f32_e32 v81, 0xbfb8aa3b, v56
	s_nop 0
	v_addc_co_u32_e32 v63, vcc, 0, v75, vcc
	global_store_short v[62:63], v76, off
	v_add_u32_e32 v76, v79, v126
	v_or3_b32 v76, v76, v149, v80
	v_ashrrev_i32_e32 v77, 31, v76
	v_lshlrev_b64 v[76:77], 6, v[76:77]
	v_or3_b32 v76, v76, v78, v127
	v_lshl_add_u64 v[76:77], v[76:77], 4, v[72:73]
	v_exp_f32_e32 v81, v81
	v_add_co_u32_e32 v82, vcc, s61, v74
	v_add_f32_e32 v81, 1.0, v81
	s_nop 0
	v_addc_co_u32_e32 v83, vcc, 0, v75, vcc
	v_mul_f32_e32 v85, 0xbfb8aa3b, v57
	v_exp_f32_e32 v85, v85
	v_rcp_f32_e32 v84, v81
	s_nop 0
	v_mul_f32_e32 v56, v56, v84
	v_add_f32_e32 v81, 1.0, v85
	s_waitcnt vmcnt(24)
	v_mov_b32_e32 v237, v141
	v_add_u32_e32 v228, v192, v178
	v_mul_hi_i32 v229, v228, s68
	v_lshrrev_b32_e32 v230, 31, v229
	v_ashrrev_i32_e32 v229, 12, v229
	v_add_u32_e32 v229, v229, v230
	v_mul_i32_i24_e32 v230, 0xffffdff0, v229
	v_add3_u32 v230, v228, v230, 48
	v_lshrrev_b32_e32 v231, 4, v230
	v_and_b32_e32 v231, 0xfffffc, v231
	v_add_lshl_u32 v232, v231, v229, 8
	v_lshlrev_b32_e32 v229, 2, v230
	v_and_b32_e32 v233, 32, v229
	v_and_b32_e32 v229, 7, v228
	v_bfe_u32 v234, v230, 4, 2
	v_lshlrev_b32_e32 v236, 1, v229
	v_lshl_add_u64 v[230:231], s[20:21], 0, v[236:237]
	v_add_u32_e32 v238, v232, v121
	v_or3_b32 v238, v238, v122, v234
	v_ashrrev_i32_e32 v239, 31, v238
	v_lshlrev_b64 v[238:239], 6, v[238:239]
	v_or3_b32 v238, v238, v233, v191
	v_lshl_add_u64 v[238:239], v[238:239], 4, v[230:231]
	global_load_dwordx2 v[224:225], v[238:239], off
	v_lshlrev_b32_e32 v86, 16, v226
	v_mul_f32_e32 v56, v56, v86
	v_mul_f32_e32 v56, v68, v56
	v_cvt_pk_bf16_f32 v56, v56, s0
	global_store_short v[74:75], v56, off offset:32
	v_and_b32_e32 v56, 0xffff0000, v226
	v_mul_f32_e32 v84, 0xbfb8aa3b, v58
	v_exp_f32_e32 v84, v84
	v_rcp_f32_e32 v76, v81
	s_nop 0
	v_mul_f32_e32 v57, v57, v76
	v_mul_f32_e32 v56, v57, v56
	v_add_f32_e32 v57, 1.0, v84
	v_mul_f32_e32 v56, v69, v56
	v_cvt_pk_bf16_f32 v56, v56, s0
	global_store_short v[82:83], v56, off offset:32
	v_mul_f32_e32 v81, 0xbfb8aa3b, v59
	v_exp_f32_e32 v81, v81
	v_lshlrev_b32_e32 v56, 16, v227
	v_rcp_f32_e32 v76, v57
	s_nop 0
	v_mul_f32_e32 v57, v58, v76
	v_mul_f32_e32 v56, v57, v56
	v_add_f32_e32 v57, 1.0, v81
	v_mul_f32_e32 v56, v70, v56
	v_cvt_pk_bf16_f32 v56, v56, s0
	global_store_short v[60:61], v56, off offset:32
	v_and_b32_e32 v56, 0xffff0000, v227
	v_rcp_f32_e32 v58, v57
	s_nop 0
	v_mul_f32_e32 v57, v59, v58
	v_mul_f32_e32 v56, v57, v56
	v_mul_f32_e32 v56, v71, v56
	v_cvt_pk_bf16_f32 v56, v56, s0
	global_store_short v[62:63], v56, off offset:32
	v_add_u32_e32 v56, v79, v121
	v_or3_b32 v56, v56, v122, v80
	v_ashrrev_i32_e32 v57, 31, v56
	v_lshlrev_b64 v[56:57], 6, v[56:57]
	v_or3_b32 v56, v56, v78, v191
	v_lshl_add_u64 v[56:57], v[56:57], 4, v[72:73]
	v_mul_f32_e32 v58, 0xbfb8aa3b, v52
	v_exp_f32_e32 v58, v58
	s_waitcnt vmcnt(24)
; DI bf16_t f2bf(float x) { return (bf16_t)(cvt_pk(x, 0.f) & 0xffffu); }
; DI size_t vf_off(int item, int dvh, int j) { return ((size_t)((item * 16 + (dvh >> 5)) * 4 + (j >> 4)) * 64 + ((j >> 3) & 1) * 32 + (dvh & 31)) * 8 + (j & 7); }
;     ...
;     } else if (EPI == EPI_E5B) {
;         const u32x2 ov = *(const u32x2*)((const bf16_t*)(p.ws + OFF_VT1) + vf_off((((pos + 48) >> 6) * 4 + b) * 4 + (col >> 9), col & 511, (pos + 48) & 63));
;         bf16_t* d = (bf16_t*)(p.ws + OFF_YB) + (size_t)row0 * 2048 + col;
; #pragma unroll
;         for (int e = 0; e < 4; ++e) {
;             const unsigned ob = (e & 1) ? (ov[e >> 1] & 0xffff0000u) : (ov[e >> 1] << 16);
;             const float o = __uint_as_float(ob);
;             const float gte = v[e] / (1.f + __expf(-v[e]));
;             d[(size_t)e * 2048] = f2bf(gte * o * s_aux[lrow0 + e]);
;         }
; template <int EPI, int K, int LNI = -1>
; DI void ph_gemm(const Params& p, const bf16_t* __restrict__ A, const bf16_t* __restrict__ Bt, int N, float* s_aux) {
;     ...
; #pragma unroll
;                     for (int bj = 0; bj < 2; ++bj)
; #pragma unroll
;                         for (int n = 0; n < 2; ++n) {
;                             float v[4];
; #pragma unroll
;                             for (int e = 0; e < 4; ++e) v[e] = acc[ai][bj][m][n][e];
;                             epi_store<EPI, LNI>(p, row0, bcol + bj * 128 + wc * 32 + n * 16 + fr + oz, lrow0, v, sa, rs, lg_[bj][n], lb_[bj][n]);
;                         }
	v_mov_b32_e32 v237, v141
	v_add_u32_e32 v228, v192, v178
	v_mul_hi_i32 v229, v228, s68
	v_lshrrev_b32_e32 v230, 31, v229
	v_ashrrev_i32_e32 v229, 12, v229
	v_add_u32_e32 v229, v229, v230
	v_mul_i32_i24_e32 v230, 0xffffdff0, v229
	v_add3_u32 v230, v228, v230, 48
	v_lshrrev_b32_e32 v231, 4, v230
	v_and_b32_e32 v231, 0xfffffc, v231
	v_add_lshl_u32 v232, v231, v229, 8
	v_lshlrev_b32_e32 v229, 2, v230
	v_and_b32_e32 v233, 32, v229
	v_and_b32_e32 v229, 7, v228
	v_bfe_u32 v234, v230, 4, 2
	v_lshlrev_b32_e32 v236, 1, v229
	v_lshl_add_u64 v[230:231], s[20:21], 0, v[236:237]
	v_add_u32_e32 v238, v232, v118
	v_or3_b32 v238, v238, v120, v234
	v_ashrrev_i32_e32 v239, 31, v238
	v_lshlrev_b64 v[238:239], 6, v[238:239]
	v_or3_b32 v238, v238, v233, v119
	v_lshl_add_u64 v[238:239], v[238:239], 4, v[230:231]
	global_load_dwordx2 v[226:227], v[238:239], off
	v_lshlrev_b32_e32 v77, 16, v216
	v_add_f32_e32 v58, 1.0, v58
	s_nop 0
	v_mul_f32_e32 v76, 0xbfb8aa3b, v53
	v_exp_f32_e32 v76, v76
	v_rcp_f32_e32 v59, v58
	s_nop 0
	v_mul_f32_e32 v52, v52, v59
	v_mul_f32_e32 v52, v52, v77
	v_mul_f32_e32 v52, v68, v52
	v_add_f32_e32 v58, 1.0, v76
	v_cvt_pk_bf16_f32 v52, v52, s0
	global_store_short v[74:75], v52, off offset:256
	v_and_b32_e32 v52, 0xffff0000, v216
	v_mul_f32_e32 v59, 0xbfb8aa3b, v54
	v_exp_f32_e32 v59, v59
	v_rcp_f32_e32 v56, v58
	s_nop 0
	v_mul_f32_e32 v53, v53, v56
	v_mul_f32_e32 v52, v53, v52
	v_add_f32_e32 v53, 1.0, v59
	v_mul_f32_e32 v52, v69, v52
	v_cvt_pk_bf16_f32 v52, v52, s0
	global_store_short v[82:83], v52, off offset:256
	v_mul_f32_e32 v58, 0xbfb8aa3b, v55
	v_exp_f32_e32 v58, v58
	v_lshlrev_b32_e32 v52, 16, v217
	v_rcp_f32_e32 v56, v53
	s_nop 0
	v_mul_f32_e32 v53, v54, v56
	v_mul_f32_e32 v52, v53, v52
	v_add_f32_e32 v53, 1.0, v58
	v_mul_f32_e32 v52, v70, v52
	v_cvt_pk_bf16_f32 v52, v52, s0
	global_store_short v[60:61], v52, off offset:256
	v_and_b32_e32 v52, 0xffff0000, v217
	v_rcp_f32_e32 v54, v53
	s_nop 0
	v_mul_f32_e32 v53, v55, v54
	v_mul_f32_e32 v52, v53, v52
	v_mul_f32_e32 v52, v71, v52
	v_cvt_pk_bf16_f32 v52, v52, s0
	global_store_short v[62:63], v52, off offset:256
	v_add_u32_e32 v52, v79, v118
	v_or3_b32 v52, v52, v120, v80
	v_ashrrev_i32_e32 v53, 31, v52
	v_lshlrev_b64 v[52:53], 6, v[52:53]
	v_or3_b32 v52, v52, v78, v119
	v_lshl_add_u64 v[52:53], v[52:53], 4, v[72:73]
	v_mul_f32_e32 v54, 0xbfb8aa3b, v48
	v_exp_f32_e32 v54, v54
	s_waitcnt vmcnt(24)
	v_mov_b32_e32 v237, v141
	v_add_u32_e32 v228, v192, v179
	v_mul_hi_i32 v229, v228, s68
	v_lshrrev_b32_e32 v230, 31, v229
	v_ashrrev_i32_e32 v229, 12, v229
	v_add_u32_e32 v229, v229, v230
	v_mul_i32_i24_e32 v230, 0xffffdff0, v229
	v_add3_u32 v230, v228, v230, 48
	v_lshrrev_b32_e32 v231, 4, v230
	v_and_b32_e32 v231, 0xfffffc, v231
	v_add_lshl_u32 v232, v231, v229, 8
	v_lshlrev_b32_e32 v229, 2, v230
	v_and_b32_e32 v233, 32, v229
	v_and_b32_e32 v229, 7, v228
	v_bfe_u32 v234, v230, 4, 2
	v_lshlrev_b32_e32 v236, 1, v229
	v_add_u32_e32 v229, v232, v193
	v_or3_b32 v230, v229, v194, v234
	v_ashrrev_i32_e32 v231, 31, v230
	v_lshlrev_b64 v[230:231], 6, v[230:231]
	v_lshl_add_u64 v[238:239], s[20:21], 0, v[236:237]
	v_or3_b32 v230, v230, v233, v191
	v_lshl_add_u64 v[230:231], v[230:231], 4, v[238:239]
	global_load_dwordx2 v[216:217], v[230:231], off
	v_lshlrev_b32_e32 v57, 16, v218
	v_add_f32_e32 v54, 1.0, v54
	s_nop 0
	v_mul_f32_e32 v56, 0xbfb8aa3b, v49
	v_exp_f32_e32 v56, v56
	v_rcp_f32_e32 v55, v54
	s_nop 0
	v_mul_f32_e32 v48, v48, v55
	v_mul_f32_e32 v48, v48, v57
	v_mul_f32_e32 v48, v68, v48
	v_add_f32_e32 v54, 1.0, v56
	v_cvt_pk_bf16_f32 v48, v48, s0
	global_store_short v[74:75], v48, off offset:288
	v_and_b32_e32 v48, 0xffff0000, v218
	v_mul_f32_e32 v55, 0xbfb8aa3b, v50
	v_exp_f32_e32 v55, v55
	v_rcp_f32_e32 v52, v54
	s_nop 0
	v_mul_f32_e32 v49, v49, v52
	v_mul_f32_e32 v48, v49, v48
	v_add_f32_e32 v49, 1.0, v55
	v_mul_f32_e32 v48, v69, v48
	v_cvt_pk_bf16_f32 v48, v48, s0
	global_store_short v[82:83], v48, off offset:288
	v_mul_f32_e32 v54, 0xbfb8aa3b, v51
	v_exp_f32_e32 v54, v54
	v_lshlrev_b32_e32 v48, 16, v219
	v_rcp_f32_e32 v52, v49
	s_nop 0
	v_mul_f32_e32 v49, v50, v52
	v_mul_f32_e32 v48, v49, v48
	v_add_f32_e32 v49, 1.0, v54
	v_mul_f32_e32 v48, v70, v48
	v_cvt_pk_bf16_f32 v48, v48, s0
	global_store_short v[60:61], v48, off offset:288
	v_and_b32_e32 v48, 0xffff0000, v219
	v_rcp_f32_e32 v50, v49
	s_nop 0
	v_mul_f32_e32 v49, v51, v50
	v_mul_f32_e32 v48, v49, v48
	v_mul_f32_e32 v48, v71, v48
	v_cvt_pk_bf16_f32 v48, v48, s0
	global_store_short v[62:63], v48, off offset:288
	v_add_u32_e32 v48, v192, v178
	v_mul_hi_i32 v49, v48, s68
	v_lshrrev_b32_e32 v50, 31, v49
	v_ashrrev_i32_e32 v49, 12, v49
	v_add_u32_e32 v49, v49, v50
	v_mul_i32_i24_e32 v50, 0xffffdff0, v49
	v_add3_u32 v50, v48, v50, 48
	v_lshrrev_b32_e32 v51, 4, v50
	v_and_b32_e32 v51, 0xfffffc, v51
	v_add_lshl_u32 v56, v51, v49, 8
	v_lshlrev_b32_e32 v49, 2, v50
	v_and_b32_e32 v58, 32, v49
	v_and_b32_e32 v49, 7, v48
	v_bfe_u32 v57, v50, 4, 2
	v_lshlrev_b32_e32 v140, 1, v49
	v_add_u32_e32 v49, v56, v193
	v_or3_b32 v52, v49, v194, v57
	v_ashrrev_i32_e32 v53, 31, v52
	v_lshlrev_b64 v[52:53], 6, v[52:53]
	v_lshl_add_u64 v[50:51], s[20:21], 0, v[140:141]
	v_or3_b32 v52, v52, v58, v191
	v_lshl_add_u64 v[52:53], v[52:53], 4, v[50:51]
	v_mul_f32_e32 v49, 0xbfb8aa3b, v44
	v_exp_f32_e32 v54, v49
	v_ashrrev_i32_e32 v49, 31, v48
	v_lshlrev_b64 v[48:49], 12, v[48:49]
	v_lshl_add_u64 v[48:49], s[36:37], 0, v[48:49]
	v_add_f32_e32 v54, 1.0, v54
	v_lshl_add_u64 v[48:49], v[48:49], 0, v[146:147]
	v_mul_f32_e32 v59, 0xbfb8aa3b, v45
	v_exp_f32_e32 v59, v59
	v_rcp_f32_e32 v55, v54
	s_nop 0
	v_mul_f32_e32 v44, v44, v55
	v_add_f32_e32 v54, 1.0, v59
	s_waitcnt vmcnt(24)
; DI bf16_t f2bf(float x) { return (bf16_t)(cvt_pk(x, 0.f) & 0xffffu); }
; DI size_t vf_off(int item, int dvh, int j) { return ((size_t)((item * 16 + (dvh >> 5)) * 4 + (j >> 4)) * 64 + ((j >> 3) & 1) * 32 + (dvh & 31)) * 8 + (j & 7); }
;     ...
;     } else if (EPI == EPI_E5B) {
;         const u32x2 ov = *(const u32x2*)((const bf16_t*)(p.ws + OFF_VT1) + vf_off((((pos + 48) >> 6) * 4 + b) * 4 + (col >> 9), col & 511, (pos + 48) & 63));
;         bf16_t* d = (bf16_t*)(p.ws + OFF_YB) + (size_t)row0 * 2048 + col;
; #pragma unroll
;         for (int e = 0; e < 4; ++e) {
;             const unsigned ob = (e & 1) ? (ov[e >> 1] & 0xffff0000u) : (ov[e >> 1] << 16);
;             const float o = __uint_as_float(ob);
;             const float gte = v[e] / (1.f + __expf(-v[e]));
;             d[(size_t)e * 2048] = f2bf(gte * o * s_aux[lrow0 + e]);
;         }
; template <int EPI, int K, int LNI = -1>
; DI void ph_gemm(const Params& p, const bf16_t* __restrict__ A, const bf16_t* __restrict__ Bt, int N, float* s_aux) {
;     ...
; #pragma unroll
;                     for (int bj = 0; bj < 2; ++bj)
; #pragma unroll
;                         for (int n = 0; n < 2; ++n) {
;                             float v[4];
; #pragma unroll
;                             for (int e = 0; e < 4; ++e) v[e] = acc[ai][bj][m][n][e];
;                             epi_store<EPI, LNI>(p, row0, bcol + bj * 128 + wc * 32 + n * 16 + fr + oz, lrow0, v, sa, rs, lg_[bj][n], lb_[bj][n]);
;                         }
	v_mov_b32_e32 v237, v141
	v_add_u32_e32 v228, v192, v179
	v_mul_hi_i32 v229, v228, s68
	v_lshrrev_b32_e32 v230, 31, v229
	v_ashrrev_i32_e32 v229, 12, v229
	v_add_u32_e32 v229, v229, v230
	v_mul_i32_i24_e32 v230, 0xffffdff0, v229
	v_add3_u32 v230, v228, v230, 48
	v_lshrrev_b32_e32 v231, 4, v230
	v_and_b32_e32 v231, 0xfffffc, v231
	v_add_lshl_u32 v232, v231, v229, 8
	v_lshlrev_b32_e32 v229, 2, v230
	v_and_b32_e32 v233, 32, v229
	v_and_b32_e32 v229, 7, v228
	v_bfe_u32 v234, v230, 4, 2
	v_lshlrev_b32_e32 v236, 1, v229
	v_lshl_add_u64 v[238:239], s[20:21], 0, v[236:237]
	v_add_u32_e32 v240, v232, v126
	v_or3_b32 v240, v240, v149, v234
	v_ashrrev_i32_e32 v241, 31, v240
	v_lshlrev_b64 v[240:241], 6, v[240:241]
	v_or3_b32 v240, v240, v233, v127
	v_lshl_add_u64 v[240:241], v[240:241], 4, v[238:239]
	global_load_dwordx2 v[218:219], v[240:241], off
	v_lshlrev_b32_e32 v60, 16, v220
	v_mul_f32_e32 v44, v44, v60
	s_waitcnt lgkmcnt(0)
	v_mul_f32_e32 v44, v64, v44
	v_cvt_pk_bf16_f32 v44, v44, s0
	global_store_short v[48:49], v44, off
	v_and_b32_e32 v44, 0xffff0000, v220
	v_rcp_f32_e32 v52, v54
	s_nop 0
	v_mul_f32_e32 v45, v45, v52
	v_mul_f32_e32 v52, 0xbfb8aa3b, v46
	v_exp_f32_e32 v52, v52
	v_mul_f32_e32 v44, v45, v44
	v_mul_f32_e32 v44, v65, v44
	v_cvt_pk_bf16_f32 v54, v44, s0
	v_add_f32_e32 v52, 1.0, v52
	v_add_co_u32_e32 v44, vcc, s3, v48
	s_nop 0
	s_nop 0
	v_addc_co_u32_e32 v45, vcc, 0, v49, vcc
	v_mul_f32_e32 v59, 0xbfb8aa3b, v47
	v_exp_f32_e32 v59, v59
	global_store_short v[44:45], v54, off offset:-4096
	v_lshlrev_b32_e32 v54, 16, v221
	v_rcp_f32_e32 v55, v52
	s_nop 0
	v_mul_f32_e32 v46, v46, v55
	v_add_f32_e32 v52, 1.0, v59
	v_mul_f32_e32 v46, v46, v54
	v_mul_f32_e32 v46, v66, v46
	v_cvt_pk_bf16_f32 v46, v46, s0
	global_store_short v[44:45], v46, off
	v_and_b32_e32 v46, 0xffff0000, v221
	v_rcp_f32_e32 v53, v52
	s_nop 0
	v_mul_f32_e32 v47, v47, v53
	v_mul_f32_e32 v46, v47, v46
	v_mul_f32_e32 v46, v67, v46
	v_cvt_pk_bf16_f32 v52, v46, s0
	v_add_co_u32_e32 v46, vcc, s69, v48
	s_nop 1
	v_addc_co_u32_e32 v47, vcc, 0, v49, vcc
	global_store_short v[46:47], v52, off
	v_add_u32_e32 v52, v56, v126
	v_or3_b32 v52, v52, v149, v57
	v_ashrrev_i32_e32 v53, 31, v52
	v_lshlrev_b64 v[52:53], 6, v[52:53]
	v_or3_b32 v52, v52, v58, v127
	v_lshl_add_u64 v[52:53], v[52:53], 4, v[50:51]
	v_mul_f32_e32 v52, 0xbfb8aa3b, v40
	v_exp_f32_e32 v52, v52
	s_waitcnt vmcnt(24)
	v_mov_b32_e32 v237, v141
	v_add_u32_e32 v228, v192, v179
	v_mul_hi_i32 v229, v228, s68
	v_lshrrev_b32_e32 v230, 31, v229
	v_ashrrev_i32_e32 v229, 12, v229
	v_add_u32_e32 v229, v229, v230
	v_mul_i32_i24_e32 v230, 0xffffdff0, v229
	v_add3_u32 v230, v228, v230, 48
	v_lshrrev_b32_e32 v231, 4, v230
	v_and_b32_e32 v231, 0xfffffc, v231
	v_add_lshl_u32 v232, v231, v229, 8
	v_lshlrev_b32_e32 v229, 2, v230
	v_and_b32_e32 v233, 32, v229
	v_and_b32_e32 v229, 7, v228
	v_bfe_u32 v234, v230, 4, 2
	v_lshlrev_b32_e32 v236, 1, v229
	v_lshl_add_u64 v[238:239], s[20:21], 0, v[236:237]
	v_add_u32_e32 v240, v232, v121
	v_or3_b32 v240, v240, v122, v234
	v_ashrrev_i32_e32 v241, 31, v240
	v_lshlrev_b64 v[240:241], 6, v[240:241]
	v_or3_b32 v240, v240, v233, v191
	v_lshl_add_u64 v[240:241], v[240:241], 4, v[238:239]
	global_load_dwordx2 v[220:221], v[240:241], off
	v_lshlrev_b32_e32 v62, 16, v222
	v_add_f32_e32 v59, 1.0, v52
	v_add_co_u32_e32 v52, vcc, s61, v48
	s_nop 0
	s_nop 0
	v_addc_co_u32_e32 v53, vcc, 0, v49, vcc
	v_mul_f32_e32 v61, 0xbfb8aa3b, v41
	v_exp_f32_e32 v61, v61
	v_rcp_f32_e32 v60, v59
	s_nop 0
	v_mul_f32_e32 v40, v40, v60
	v_mul_f32_e32 v40, v40, v62
	v_mul_f32_e32 v40, v64, v40
	v_add_f32_e32 v59, 1.0, v61
	v_cvt_pk_bf16_f32 v40, v40, s0
	global_store_short v[48:49], v40, off offset:32
	v_and_b32_e32 v40, 0xffff0000, v222
	v_mul_f32_e32 v60, 0xbfb8aa3b, v42
	v_exp_f32_e32 v60, v60
	v_rcp_f32_e32 v54, v59
	s_nop 0
	v_mul_f32_e32 v41, v41, v54
	v_mul_f32_e32 v40, v41, v40
	v_add_f32_e32 v41, 1.0, v60
	v_mul_f32_e32 v40, v65, v40
	v_cvt_pk_bf16_f32 v40, v40, s0
	global_store_short v[52:53], v40, off offset:32
	v_mul_f32_e32 v59, 0xbfb8aa3b, v43
	v_exp_f32_e32 v59, v59
	v_lshlrev_b32_e32 v40, 16, v223
	v_rcp_f32_e32 v54, v41
	s_nop 0
	v_mul_f32_e32 v41, v42, v54
	v_mul_f32_e32 v40, v41, v40
	v_add_f32_e32 v41, 1.0, v59
	v_mul_f32_e32 v40, v66, v40
	v_cvt_pk_bf16_f32 v40, v40, s0
	global_store_short v[44:45], v40, off offset:32
	v_and_b32_e32 v40, 0xffff0000, v223
	v_rcp_f32_e32 v42, v41
	s_nop 0
	v_mul_f32_e32 v41, v43, v42
	v_mul_f32_e32 v40, v41, v40
	v_mul_f32_e32 v40, v67, v40
	v_cvt_pk_bf16_f32 v40, v40, s0
	global_store_short v[46:47], v40, off offset:32
	v_add_u32_e32 v40, v56, v121
	v_or3_b32 v40, v40, v122, v57
	v_ashrrev_i32_e32 v41, 31, v40
	v_lshlrev_b64 v[40:41], 6, v[40:41]
	v_or3_b32 v40, v40, v58, v191
	v_lshl_add_u64 v[40:41], v[40:41], 4, v[50:51]
	v_mul_f32_e32 v42, 0xbfb8aa3b, v36
	v_exp_f32_e32 v42, v42
	s_waitcnt vmcnt(24)
; DI bf16_t f2bf(float x) { return (bf16_t)(cvt_pk(x, 0.f) & 0xffffu); }
; DI size_t vf_off(int item, int dvh, int j) { return ((size_t)((item * 16 + (dvh >> 5)) * 4 + (j >> 4)) * 64 + ((j >> 3) & 1) * 32 + (dvh & 31)) * 8 + (j & 7); }
;     ...
;     } else if (EPI == EPI_E5B) {
;         const u32x2 ov = *(const u32x2*)((const bf16_t*)(p.ws + OFF_VT1) + vf_off((((pos + 48) >> 6) * 4 + b) * 4 + (col >> 9), col & 511, (pos + 48) & 63));
;         bf16_t* d = (bf16_t*)(p.ws + OFF_YB) + (size_t)row0 * 2048 + col;
; #pragma unroll
;         for (int e = 0; e < 4; ++e) {
;             const unsigned ob = (e & 1) ? (ov[e >> 1] & 0xffff0000u) : (ov[e >> 1] << 16);
;             const float o = __uint_as_float(ob);
;             const float gte = v[e] / (1.f + __expf(-v[e]));
;             d[(size_t)e * 2048] = f2bf(gte * o * s_aux[lrow0 + e]);
;         }
; template <int EPI, int K, int LNI = -1>
; DI void ph_gemm(const Params& p, const bf16_t* __restrict__ A, const bf16_t* __restrict__ Bt, int N, float* s_aux) {
;     ...
; #pragma unroll
;                     for (int bj = 0; bj < 2; ++bj)
; #pragma unroll
;                         for (int n = 0; n < 2; ++n) {
;                             float v[4];
; #pragma unroll
;                             for (int e = 0; e < 4; ++e) v[e] = acc[ai][bj][m][n][e];
;                             epi_store<EPI, LNI>(p, row0, bcol + bj * 128 + wc * 32 + n * 16 + fr + oz, lrow0, v, sa, rs, lg_[bj][n], lb_[bj][n]);
;                         }
	v_mov_b32_e32 v237, v141
	v_add_u32_e32 v228, v192, v179
	v_mul_hi_i32 v229, v228, s68
	v_lshrrev_b32_e32 v230, 31, v229
	v_ashrrev_i32_e32 v229, 12, v229
	v_add_u32_e32 v229, v229, v230
	v_mul_i32_i24_e32 v230, 0xffffdff0, v229
	v_add3_u32 v230, v228, v230, 48
	v_lshrrev_b32_e32 v231, 4, v230
	v_and_b32_e32 v231, 0xfffffc, v231
	v_add_lshl_u32 v232, v231, v229, 8
	v_lshlrev_b32_e32 v229, 2, v230
	v_and_b32_e32 v233, 32, v229
	v_and_b32_e32 v229, 7, v228
	v_bfe_u32 v234, v230, 4, 2
	v_lshlrev_b32_e32 v236, 1, v229
	v_lshl_add_u64 v[238:239], s[20:21], 0, v[236:237]
	v_add_u32_e32 v240, v232, v118
	v_or3_b32 v240, v240, v120, v234
	v_ashrrev_i32_e32 v241, 31, v240
	v_lshlrev_b64 v[240:241], 6, v[240:241]
	v_or3_b32 v240, v240, v233, v119
	v_lshl_add_u64 v[240:241], v[240:241], 4, v[238:239]
	global_load_dwordx2 v[222:223], v[240:241], off
	v_lshlrev_b32_e32 v55, 16, v224
	v_add_f32_e32 v42, 1.0, v42
	s_nop 0
	v_mul_f32_e32 v54, 0xbfb8aa3b, v37
	v_exp_f32_e32 v54, v54
	v_rcp_f32_e32 v43, v42
	s_nop 0
	v_mul_f32_e32 v36, v36, v43
	v_mul_f32_e32 v36, v36, v55
	v_mul_f32_e32 v36, v64, v36
	v_add_f32_e32 v42, 1.0, v54
	v_cvt_pk_bf16_f32 v36, v36, s0
	global_store_short v[48:49], v36, off offset:256
	v_and_b32_e32 v36, 0xffff0000, v224
	v_mul_f32_e32 v43, 0xbfb8aa3b, v38
	v_exp_f32_e32 v43, v43
	v_rcp_f32_e32 v40, v42
	s_nop 0
	v_mul_f32_e32 v37, v37, v40
	v_mul_f32_e32 v36, v37, v36
	v_add_f32_e32 v37, 1.0, v43
	v_mul_f32_e32 v36, v65, v36
	v_cvt_pk_bf16_f32 v36, v36, s0
	global_store_short v[52:53], v36, off offset:256
	v_mul_f32_e32 v42, 0xbfb8aa3b, v39
	v_exp_f32_e32 v42, v42
	v_lshlrev_b32_e32 v36, 16, v225
	v_rcp_f32_e32 v40, v37
	s_nop 0
	v_mul_f32_e32 v37, v38, v40
	v_mul_f32_e32 v36, v37, v36
	v_add_f32_e32 v37, 1.0, v42
	v_mul_f32_e32 v36, v66, v36
	v_cvt_pk_bf16_f32 v36, v36, s0
	global_store_short v[44:45], v36, off offset:256
	v_and_b32_e32 v36, 0xffff0000, v225
	v_rcp_f32_e32 v38, v37
	s_nop 0
	v_mul_f32_e32 v37, v39, v38
	v_mul_f32_e32 v36, v37, v36
	v_mul_f32_e32 v36, v67, v36
	v_cvt_pk_bf16_f32 v36, v36, s0
	global_store_short v[46:47], v36, off offset:256
	v_add_u32_e32 v36, v56, v118
	v_or3_b32 v36, v36, v120, v57
	v_ashrrev_i32_e32 v37, 31, v36
	v_lshlrev_b64 v[36:37], 6, v[36:37]
	v_or3_b32 v36, v36, v58, v119
	v_lshl_add_u64 v[36:37], v[36:37], 4, v[50:51]
	v_mul_f32_e32 v38, 0xbfb8aa3b, v32
	v_exp_f32_e32 v38, v38
	s_waitcnt vmcnt(24)
	v_mov_b32_e32 v237, v141
	v_add_u32_e32 v228, v192, v180
	v_mul_hi_i32 v229, v228, s68
	v_lshrrev_b32_e32 v230, 31, v229
	v_ashrrev_i32_e32 v229, 12, v229
	v_add_u32_e32 v229, v229, v230
	v_mul_i32_i24_e32 v230, 0xffffdff0, v229
	v_add3_u32 v230, v228, v230, 48
	v_lshrrev_b32_e32 v231, 4, v230
	v_and_b32_e32 v231, 0xfffffc, v231
	v_add_lshl_u32 v232, v231, v229, 8
	v_lshlrev_b32_e32 v229, 2, v230
	v_and_b32_e32 v233, 32, v229
	v_and_b32_e32 v229, 7, v228
	v_bfe_u32 v234, v230, 4, 2
	v_lshlrev_b32_e32 v236, 1, v229
	v_add_u32_e32 v229, v232, v193
	v_or3_b32 v238, v229, v194, v234
	v_ashrrev_i32_e32 v239, 31, v238
	v_lshlrev_b64 v[238:239], 6, v[238:239]
	v_lshl_add_u64 v[230:231], s[20:21], 0, v[236:237]
	v_or3_b32 v238, v238, v233, v191
	v_lshl_add_u64 v[238:239], v[238:239], 4, v[230:231]
	global_load_dwordx2 v[224:225], v[238:239], off
	v_lshlrev_b32_e32 v41, 16, v226
	v_add_f32_e32 v38, 1.0, v38
	s_nop 0
	v_mul_f32_e32 v40, 0xbfb8aa3b, v33
	v_exp_f32_e32 v40, v40
	v_rcp_f32_e32 v39, v38
	s_nop 0
	v_mul_f32_e32 v32, v32, v39
	v_mul_f32_e32 v32, v32, v41
	v_mul_f32_e32 v32, v64, v32
	v_add_f32_e32 v38, 1.0, v40
	v_cvt_pk_bf16_f32 v32, v32, s0
	global_store_short v[48:49], v32, off offset:288
	v_and_b32_e32 v32, 0xffff0000, v226
	v_mul_f32_e32 v39, 0xbfb8aa3b, v34
	v_exp_f32_e32 v39, v39
	v_rcp_f32_e32 v36, v38
	s_nop 0
	v_mul_f32_e32 v33, v33, v36
	v_mul_f32_e32 v32, v33, v32
	v_add_f32_e32 v33, 1.0, v39
	v_mul_f32_e32 v32, v65, v32
	v_cvt_pk_bf16_f32 v32, v32, s0
	global_store_short v[52:53], v32, off offset:288
	v_mul_f32_e32 v38, 0xbfb8aa3b, v35
	v_exp_f32_e32 v38, v38
	v_lshlrev_b32_e32 v32, 16, v227
	v_rcp_f32_e32 v36, v33
	s_nop 0
	v_mul_f32_e32 v33, v34, v36
	v_mul_f32_e32 v32, v33, v32
	v_add_f32_e32 v33, 1.0, v38
	v_mul_f32_e32 v32, v66, v32
	v_cvt_pk_bf16_f32 v32, v32, s0
	global_store_short v[44:45], v32, off offset:288
	v_and_b32_e32 v32, 0xffff0000, v227
	v_rcp_f32_e32 v34, v33
	s_nop 0
	v_mul_f32_e32 v33, v35, v34
	v_mul_f32_e32 v32, v33, v32
	v_mul_f32_e32 v32, v67, v32
	v_cvt_pk_bf16_f32 v32, v32, s0
	global_store_short v[46:47], v32, off offset:288
	v_add_u32_e32 v32, v192, v179
	v_mul_hi_i32 v33, v32, s68
	v_lshrrev_b32_e32 v34, 31, v33
	v_ashrrev_i32_e32 v33, 12, v33
	v_add_u32_e32 v33, v33, v34
	v_mul_i32_i24_e32 v34, 0xffffdff0, v33
	v_add3_u32 v34, v32, v34, 48
	v_lshrrev_b32_e32 v35, 4, v34
	v_and_b32_e32 v35, 0xfffffc, v35
	v_add_lshl_u32 v47, v35, v33, 8
	v_lshlrev_b32_e32 v33, 2, v34
	v_and_b32_e32 v46, 32, v33
	v_and_b32_e32 v33, 7, v32
	v_bfe_u32 v48, v34, 4, 2
	v_lshlrev_b32_e32 v140, 1, v33
	v_add_u32_e32 v33, v47, v193
	v_or3_b32 v34, v33, v194, v48
	v_ashrrev_i32_e32 v35, 31, v34
	v_lshlrev_b64 v[34:35], 6, v[34:35]
	v_lshl_add_u64 v[40:41], s[20:21], 0, v[140:141]
	v_or3_b32 v34, v34, v46, v191
	v_lshl_add_u64 v[34:35], v[34:35], 4, v[40:41]
	v_mul_f32_e32 v33, 0xbfb8aa3b, v28
	v_exp_f32_e32 v34, v33
	v_ashrrev_i32_e32 v33, 31, v32
	v_lshlrev_b64 v[32:33], 12, v[32:33]
	v_lshl_add_u64 v[32:33], s[36:37], 0, v[32:33]
	v_add_f32_e32 v34, 1.0, v34
	v_lshl_add_u64 v[42:43], v[32:33], 0, v[146:147]
	ds_read_b128 v[36:39], v195 offset:640
	v_rcp_f32_e32 v33, v34
	s_nop 0
	v_mul_f32_e32 v28, v28, v33
	v_mul_f32_e32 v33, 0xbfb8aa3b, v29
	v_exp_f32_e32 v49, v33
	s_waitcnt vmcnt(24)
; DI bf16_t f2bf(float x) { return (bf16_t)(cvt_pk(x, 0.f) & 0xffffu); }
; DI size_t vf_off(int item, int dvh, int j) { return ((size_t)((item * 16 + (dvh >> 5)) * 4 + (j >> 4)) * 64 + ((j >> 3) & 1) * 32 + (dvh & 31)) * 8 + (j & 7); }
;     ...
;     } else if (EPI == EPI_E5B) {
;         const u32x2 ov = *(const u32x2*)((const bf16_t*)(p.ws + OFF_VT1) + vf_off((((pos + 48) >> 6) * 4 + b) * 4 + (col >> 9), col & 511, (pos + 48) & 63));
;         bf16_t* d = (bf16_t*)(p.ws + OFF_YB) + (size_t)row0 * 2048 + col;
; #pragma unroll
;         for (int e = 0; e < 4; ++e) {
;             const unsigned ob = (e & 1) ? (ov[e >> 1] & 0xffff0000u) : (ov[e >> 1] << 16);
;             const float o = __uint_as_float(ob);
;             const float gte = v[e] / (1.f + __expf(-v[e]));
;             d[(size_t)e * 2048] = f2bf(gte * o * s_aux[lrow0 + e]);
;         }
; template <int EPI, int K, int LNI = -1>
; DI void ph_gemm(const Params& p, const bf16_t* __restrict__ A, const bf16_t* __restrict__ Bt, int N, float* s_aux) {
;     ...
; #pragma unroll
;                     for (int bj = 0; bj < 2; ++bj)
; #pragma unroll
;                         for (int n = 0; n < 2; ++n) {
;                             float v[4];
; #pragma unroll
;                             for (int e = 0; e < 4; ++e) v[e] = acc[ai][bj][m][n][e];
;                             epi_store<EPI, LNI>(p, row0, bcol + bj * 128 + wc * 32 + n * 16 + fr + oz, lrow0, v, sa, rs, lg_[bj][n], lb_[bj][n]);
;                         }
	v_mov_b32_e32 v237, v141
	v_add_u32_e32 v228, v192, v180
	v_mul_hi_i32 v229, v228, s68
	v_lshrrev_b32_e32 v230, 31, v229
	v_ashrrev_i32_e32 v229, 12, v229
	v_add_u32_e32 v229, v229, v230
	v_mul_i32_i24_e32 v230, 0xffffdff0, v229
	v_add3_u32 v230, v228, v230, 48
	v_lshrrev_b32_e32 v231, 4, v230
	v_and_b32_e32 v231, 0xfffffc, v231
	v_add_lshl_u32 v232, v231, v229, 8
	v_lshlrev_b32_e32 v229, 2, v230
	v_and_b32_e32 v233, 32, v229
	v_and_b32_e32 v229, 7, v228
	v_bfe_u32 v234, v230, 4, 2
	v_lshlrev_b32_e32 v236, 1, v229
	v_lshl_add_u64 v[230:231], s[20:21], 0, v[236:237]
	v_add_u32_e32 v238, v232, v126
	v_or3_b32 v238, v238, v149, v234
	v_ashrrev_i32_e32 v239, 31, v238
	v_lshlrev_b64 v[238:239], 6, v[238:239]
	v_or3_b32 v238, v238, v233, v127
	v_lshl_add_u64 v[238:239], v[238:239], 4, v[230:231]
	global_load_dwordx2 v[226:227], v[238:239], off
	v_lshlrev_b32_e32 v32, 16, v216
	v_add_f32_e32 v49, 1.0, v49
	v_mul_f32_e32 v28, v28, v32
	ds_read_b128 v[32:35], v195 offset:704
	s_waitcnt lgkmcnt(1)
	v_mul_f32_e32 v28, v36, v28
	v_cvt_pk_bf16_f32 v28, v28, s0
	global_store_short v[42:43], v28, off
	v_and_b32_e32 v28, 0xffff0000, v216
	v_rcp_f32_e32 v44, v49
	s_nop 0
	v_mul_f32_e32 v29, v29, v44
	v_mul_f32_e32 v44, 0xbfb8aa3b, v30
	v_exp_f32_e32 v44, v44
	v_mul_f32_e32 v28, v29, v28
	v_mul_f32_e32 v28, v37, v28
	v_cvt_pk_bf16_f32 v49, v28, s0
	v_add_f32_e32 v44, 1.0, v44
	v_add_co_u32_e32 v28, vcc, s3, v42
	s_nop 0
	s_nop 0
	v_addc_co_u32_e32 v29, vcc, 0, v43, vcc
	v_mul_f32_e32 v51, 0xbfb8aa3b, v31
	v_exp_f32_e32 v51, v51
	global_store_short v[28:29], v49, off offset:-4096
	v_lshlrev_b32_e32 v49, 16, v217
	v_rcp_f32_e32 v50, v44
	s_nop 0
	v_mul_f32_e32 v30, v30, v50
	v_add_f32_e32 v44, 1.0, v51
	v_mul_f32_e32 v30, v30, v49
	v_mul_f32_e32 v30, v38, v30
	v_cvt_pk_bf16_f32 v30, v30, s0
	global_store_short v[28:29], v30, off
	v_and_b32_e32 v30, 0xffff0000, v217
	v_rcp_f32_e32 v45, v44
	s_nop 0
	v_mul_f32_e32 v31, v31, v45
	v_mul_f32_e32 v30, v31, v30
	v_mul_f32_e32 v30, v39, v30
	v_cvt_pk_bf16_f32 v44, v30, s0
	v_add_co_u32_e32 v30, vcc, s69, v42
	v_mul_f32_e32 v49, 0xbfb8aa3b, v24
	s_nop 0
	v_addc_co_u32_e32 v31, vcc, 0, v43, vcc
	global_store_short v[30:31], v44, off
	v_add_u32_e32 v44, v47, v126
	v_or3_b32 v44, v44, v149, v48
	v_ashrrev_i32_e32 v45, 31, v44
	v_lshlrev_b64 v[44:45], 6, v[44:45]
	v_or3_b32 v44, v44, v46, v127
	v_lshl_add_u64 v[44:45], v[44:45], 4, v[40:41]
	v_exp_f32_e32 v49, v49
	v_add_co_u32_e32 v50, vcc, s61, v42
	v_add_f32_e32 v49, 1.0, v49
	s_nop 0
	v_addc_co_u32_e32 v51, vcc, 0, v43, vcc
	v_mul_f32_e32 v53, 0xbfb8aa3b, v25
	v_exp_f32_e32 v53, v53
	v_rcp_f32_e32 v52, v49
	s_nop 0
	v_mul_f32_e32 v24, v24, v52
	v_add_f32_e32 v49, 1.0, v53
	s_waitcnt vmcnt(24)
	v_mov_b32_e32 v237, v141
	v_add_u32_e32 v228, v192, v180
	v_mul_hi_i32 v229, v228, s68
	v_lshrrev_b32_e32 v230, 31, v229
	v_ashrrev_i32_e32 v229, 12, v229
	v_add_u32_e32 v229, v229, v230
	v_mul_i32_i24_e32 v230, 0xffffdff0, v229
	v_add3_u32 v230, v228, v230, 48
	v_lshrrev_b32_e32 v231, 4, v230
	v_and_b32_e32 v231, 0xfffffc, v231
	v_add_lshl_u32 v232, v231, v229, 8
	v_lshlrev_b32_e32 v229, 2, v230
	v_and_b32_e32 v233, 32, v229
	v_and_b32_e32 v229, 7, v228
	v_bfe_u32 v234, v230, 4, 2
	v_lshlrev_b32_e32 v236, 1, v229
	v_lshl_add_u64 v[230:231], s[20:21], 0, v[236:237]
	v_add_u32_e32 v238, v232, v121
	v_or3_b32 v238, v238, v122, v234
	v_ashrrev_i32_e32 v239, 31, v238
	v_lshlrev_b64 v[238:239], 6, v[238:239]
	v_or3_b32 v238, v238, v233, v191
	v_lshl_add_u64 v[238:239], v[238:239], 4, v[230:231]
	global_load_dwordx2 v[216:217], v[238:239], off
	v_lshlrev_b32_e32 v54, 16, v218
	v_mul_f32_e32 v24, v24, v54
	v_mul_f32_e32 v24, v36, v24
	v_cvt_pk_bf16_f32 v24, v24, s0
	global_store_short v[42:43], v24, off offset:32
	v_and_b32_e32 v24, 0xffff0000, v218
	v_mul_f32_e32 v52, 0xbfb8aa3b, v26
	v_exp_f32_e32 v52, v52
	v_rcp_f32_e32 v44, v49
	s_nop 0
	v_mul_f32_e32 v25, v25, v44
	v_mul_f32_e32 v24, v25, v24
	v_add_f32_e32 v25, 1.0, v52
	v_mul_f32_e32 v24, v37, v24
	v_cvt_pk_bf16_f32 v24, v24, s0
	global_store_short v[50:51], v24, off offset:32
	v_mul_f32_e32 v49, 0xbfb8aa3b, v27
	v_exp_f32_e32 v49, v49
	v_lshlrev_b32_e32 v24, 16, v219
	v_rcp_f32_e32 v44, v25
	s_nop 0
	v_mul_f32_e32 v25, v26, v44
	v_mul_f32_e32 v24, v25, v24
	v_add_f32_e32 v25, 1.0, v49
	v_mul_f32_e32 v24, v38, v24
	v_cvt_pk_bf16_f32 v24, v24, s0
	global_store_short v[28:29], v24, off offset:32
	v_and_b32_e32 v24, 0xffff0000, v219
	v_rcp_f32_e32 v26, v25
	s_nop 0
	v_mul_f32_e32 v25, v27, v26
	v_mul_f32_e32 v24, v25, v24
	v_mul_f32_e32 v24, v39, v24
	v_cvt_pk_bf16_f32 v24, v24, s0
	global_store_short v[30:31], v24, off offset:32
	v_add_u32_e32 v24, v47, v121
	v_or3_b32 v24, v24, v122, v48
	v_ashrrev_i32_e32 v25, 31, v24
	v_lshlrev_b64 v[24:25], 6, v[24:25]
	v_or3_b32 v24, v24, v46, v191
	v_lshl_add_u64 v[24:25], v[24:25], 4, v[40:41]
	v_mul_f32_e32 v26, 0xbfb8aa3b, v20
	v_exp_f32_e32 v26, v26
	s_waitcnt vmcnt(24)
; DI bf16_t f2bf(float x) { return (bf16_t)(cvt_pk(x, 0.f) & 0xffffu); }
; DI size_t vf_off(int item, int dvh, int j) { return ((size_t)((item * 16 + (dvh >> 5)) * 4 + (j >> 4)) * 64 + ((j >> 3) & 1) * 32 + (dvh & 31)) * 8 + (j & 7); }
;     ...
;     } else if (EPI == EPI_E5B) {
;         const u32x2 ov = *(const u32x2*)((const bf16_t*)(p.ws + OFF_VT1) + vf_off((((pos + 48) >> 6) * 4 + b) * 4 + (col >> 9), col & 511, (pos + 48) & 63));
;         bf16_t* d = (bf16_t*)(p.ws + OFF_YB) + (size_t)row0 * 2048 + col;
; #pragma unroll
;         for (int e = 0; e < 4; ++e) {
;             const unsigned ob = (e & 1) ? (ov[e >> 1] & 0xffff0000u) : (ov[e >> 1] << 16);
;             const float o = __uint_as_float(ob);
;             const float gte = v[e] / (1.f + __expf(-v[e]));
;             d[(size_t)e * 2048] = f2bf(gte * o * s_aux[lrow0 + e]);
;         }
; template <int EPI, int K, int LNI = -1>
; DI void ph_gemm(const Params& p, const bf16_t* __restrict__ A, const bf16_t* __restrict__ Bt, int N, float* s_aux) {
;     ...
; #pragma unroll
;                     for (int bj = 0; bj < 2; ++bj)
; #pragma unroll
;                         for (int n = 0; n < 2; ++n) {
;                             float v[4];
; #pragma unroll
;                             for (int e = 0; e < 4; ++e) v[e] = acc[ai][bj][m][n][e];
;                             epi_store<EPI, LNI>(p, row0, bcol + bj * 128 + wc * 32 + n * 16 + fr + oz, lrow0, v, sa, rs, lg_[bj][n], lb_[bj][n]);
;                         }
	v_mov_b32_e32 v237, v141
	v_add_u32_e32 v228, v192, v180
	v_mul_hi_i32 v229, v228, s68
	v_lshrrev_b32_e32 v230, 31, v229
	v_ashrrev_i32_e32 v229, 12, v229
	v_add_u32_e32 v229, v229, v230
	v_mul_i32_i24_e32 v230, 0xffffdff0, v229
	v_add3_u32 v230, v228, v230, 48
	v_lshrrev_b32_e32 v231, 4, v230
	v_and_b32_e32 v231, 0xfffffc, v231
	v_add_lshl_u32 v232, v231, v229, 8
	v_lshlrev_b32_e32 v229, 2, v230
	v_and_b32_e32 v233, 32, v229
	v_and_b32_e32 v229, 7, v228
	v_bfe_u32 v234, v230, 4, 2
	v_lshlrev_b32_e32 v236, 1, v229
	v_lshl_add_u64 v[230:231], s[20:21], 0, v[236:237]
	v_add_u32_e32 v238, v232, v118
	v_or3_b32 v238, v238, v120, v234
	v_ashrrev_i32_e32 v239, 31, v238
	v_lshlrev_b64 v[238:239], 6, v[238:239]
	v_or3_b32 v238, v238, v233, v119
	v_lshl_add_u64 v[238:239], v[238:239], 4, v[230:231]
	global_load_dwordx2 v[218:219], v[238:239], off
	v_lshlrev_b32_e32 v45, 16, v220
	v_add_f32_e32 v26, 1.0, v26
	s_nop 0
	v_mul_f32_e32 v44, 0xbfb8aa3b, v21
	v_exp_f32_e32 v44, v44
	v_rcp_f32_e32 v27, v26
	s_nop 0
	v_mul_f32_e32 v20, v20, v27
	v_mul_f32_e32 v20, v20, v45
	v_mul_f32_e32 v20, v36, v20
	v_add_f32_e32 v26, 1.0, v44
	v_cvt_pk_bf16_f32 v20, v20, s0
	global_store_short v[42:43], v20, off offset:256
	v_and_b32_e32 v20, 0xffff0000, v220
	v_mul_f32_e32 v27, 0xbfb8aa3b, v22
	v_exp_f32_e32 v27, v27
	v_rcp_f32_e32 v24, v26
	s_nop 0
	v_mul_f32_e32 v21, v21, v24
	v_mul_f32_e32 v20, v21, v20
	v_add_f32_e32 v21, 1.0, v27
	v_mul_f32_e32 v20, v37, v20
	v_cvt_pk_bf16_f32 v20, v20, s0
	global_store_short v[50:51], v20, off offset:256
	v_mul_f32_e32 v26, 0xbfb8aa3b, v23
	v_exp_f32_e32 v26, v26
	v_lshlrev_b32_e32 v20, 16, v221
	v_rcp_f32_e32 v24, v21
	s_nop 0
	v_mul_f32_e32 v21, v22, v24
	v_mul_f32_e32 v20, v21, v20
	v_add_f32_e32 v21, 1.0, v26
	v_mul_f32_e32 v20, v38, v20
	v_cvt_pk_bf16_f32 v20, v20, s0
	global_store_short v[28:29], v20, off offset:256
	v_and_b32_e32 v20, 0xffff0000, v221
	v_rcp_f32_e32 v22, v21
	s_nop 0
	v_mul_f32_e32 v21, v23, v22
	v_mul_f32_e32 v20, v21, v20
	v_mul_f32_e32 v20, v39, v20
	v_cvt_pk_bf16_f32 v20, v20, s0
	global_store_short v[30:31], v20, off offset:256
	v_add_u32_e32 v20, v47, v118
	v_or3_b32 v20, v20, v120, v48
	v_ashrrev_i32_e32 v21, 31, v20
	v_lshlrev_b64 v[20:21], 6, v[20:21]
	v_or3_b32 v20, v20, v46, v119
	v_lshl_add_u64 v[20:21], v[20:21], 4, v[40:41]
	v_mul_f32_e32 v22, 0xbfb8aa3b, v16
	v_exp_f32_e32 v22, v22
	s_waitcnt vmcnt(24)
	v_lshlrev_b32_e32 v25, 16, v222
	v_add_f32_e32 v22, 1.0, v22
	s_nop 0
	v_mul_f32_e32 v24, 0xbfb8aa3b, v17
	v_exp_f32_e32 v24, v24
	v_rcp_f32_e32 v23, v22
	s_nop 0
	v_mul_f32_e32 v16, v16, v23
	v_mul_f32_e32 v16, v16, v25
	v_mul_f32_e32 v16, v36, v16
	v_add_f32_e32 v22, 1.0, v24
	v_cvt_pk_bf16_f32 v16, v16, s0
	global_store_short v[42:43], v16, off offset:288
	v_and_b32_e32 v16, 0xffff0000, v222
	v_mul_f32_e32 v23, 0xbfb8aa3b, v18
	v_exp_f32_e32 v23, v23
	v_rcp_f32_e32 v20, v22
	s_nop 0
	v_mul_f32_e32 v17, v17, v20
	v_mul_f32_e32 v16, v17, v16
	v_add_f32_e32 v17, 1.0, v23
	v_mul_f32_e32 v16, v37, v16
	v_cvt_pk_bf16_f32 v16, v16, s0
	global_store_short v[50:51], v16, off offset:288
	v_mul_f32_e32 v22, 0xbfb8aa3b, v19
	v_exp_f32_e32 v22, v22
	v_lshlrev_b32_e32 v16, 16, v223
	v_rcp_f32_e32 v20, v17
	s_nop 0
	v_mul_f32_e32 v17, v18, v20
	v_mul_f32_e32 v16, v17, v16
	v_add_f32_e32 v17, 1.0, v22
	v_mul_f32_e32 v16, v38, v16
	v_cvt_pk_bf16_f32 v16, v16, s0
	global_store_short v[28:29], v16, off offset:288
	v_and_b32_e32 v16, 0xffff0000, v223
	v_rcp_f32_e32 v18, v17
	s_nop 0
	v_mul_f32_e32 v17, v19, v18
	v_mul_f32_e32 v16, v17, v16
	v_mul_f32_e32 v16, v39, v16
	v_cvt_pk_bf16_f32 v16, v16, s0
	global_store_short v[30:31], v16, off offset:288
	v_add_u32_e32 v16, v192, v180
	v_mul_hi_i32 v17, v16, s68
	v_lshrrev_b32_e32 v18, 31, v17
	v_ashrrev_i32_e32 v17, 12, v17
	v_add_u32_e32 v17, v17, v18
	v_mul_i32_i24_e32 v18, 0xffffdff0, v17
	v_add3_u32 v18, v16, v18, 48
	v_lshrrev_b32_e32 v19, 4, v18
	v_and_b32_e32 v19, 0xfffffc, v19
	v_add_lshl_u32 v24, v19, v17, 8
	v_lshlrev_b32_e32 v17, 2, v18
	v_and_b32_e32 v26, 32, v17
	v_and_b32_e32 v17, 7, v16
	v_bfe_u32 v25, v18, 4, 2
	v_lshlrev_b32_e32 v140, 1, v17
	v_add_u32_e32 v17, v24, v193
	v_or3_b32 v20, v17, v194, v25
	v_ashrrev_i32_e32 v21, 31, v20
	v_lshlrev_b64 v[20:21], 6, v[20:21]
	v_lshl_add_u64 v[18:19], s[20:21], 0, v[140:141]
	v_or3_b32 v20, v20, v26, v191
	v_lshl_add_u64 v[20:21], v[20:21], 4, v[18:19]
	v_mul_f32_e32 v17, 0xbfb8aa3b, v12
	v_exp_f32_e32 v22, v17
	v_ashrrev_i32_e32 v17, 31, v16
	v_lshlrev_b64 v[16:17], 12, v[16:17]
	v_lshl_add_u64 v[16:17], s[36:37], 0, v[16:17]
	v_add_f32_e32 v22, 1.0, v22
	v_lshl_add_u64 v[16:17], v[16:17], 0, v[146:147]
	v_mul_f32_e32 v27, 0xbfb8aa3b, v13
	v_exp_f32_e32 v27, v27
	v_rcp_f32_e32 v23, v22
	s_nop 0
	v_mul_f32_e32 v12, v12, v23
	v_add_f32_e32 v22, 1.0, v27
	s_waitcnt vmcnt(23)
	v_lshlrev_b32_e32 v28, 16, v224
	v_mul_f32_e32 v12, v12, v28
	s_waitcnt lgkmcnt(0)
; DI bf16_t f2bf(float x) { return (bf16_t)(cvt_pk(x, 0.f) & 0xffffu); }
; DI size_t vf_off(int item, int dvh, int j) { return ((size_t)((item * 16 + (dvh >> 5)) * 4 + (j >> 4)) * 64 + ((j >> 3) & 1) * 32 + (dvh & 31)) * 8 + (j & 7); }
; #define BAR __builtin_amdgcn_s_barrier()
;     ...
;     } else if (EPI == EPI_E5B) {
;         const u32x2 ov = *(const u32x2*)((const bf16_t*)(p.ws + OFF_VT1) + vf_off((((pos + 48) >> 6) * 4 + b) * 4 + (col >> 9), col & 511, (pos + 48) & 63));
;         bf16_t* d = (bf16_t*)(p.ws + OFF_YB) + (size_t)row0 * 2048 + col;
; #pragma unroll
;         for (int e = 0; e < 4; ++e) {
;             const unsigned ob = (e & 1) ? (ov[e >> 1] & 0xffff0000u) : (ov[e >> 1] << 16);
;             const float o = __uint_as_float(ob);
;             const float gte = v[e] / (1.f + __expf(-v[e]));
;             d[(size_t)e * 2048] = f2bf(gte * o * s_aux[lrow0 + e]);
;         }
; template <int EPI, int K, int LNI = -1>
; DI void ph_gemm(const Params& p, const bf16_t* __restrict__ A, const bf16_t* __restrict__ Bt, int N, float* s_aux) {
;     ...
; #pragma unroll
;                     for (int bj = 0; bj < 2; ++bj)
; #pragma unroll
;                         for (int n = 0; n < 2; ++n) {
;                             float v[4];
; #pragma unroll
;                             for (int e = 0; e < 4; ++e) v[e] = acc[ai][bj][m][n][e];
;                             epi_store<EPI, LNI>(p, row0, bcol + bj * 128 + wc * 32 + n * 16 + fr + oz, lrow0, v, sa, rs, lg_[bj][n], lb_[bj][n]);
;                         }
;                 }
;         }
;         if (!has_next) break;
; #pragma unroll
;         for (int a = 0; a < 2; ++a)
; #pragma unroll
;             for (int b = 0; b < 2; ++b)
; #pragma unroll
;                 for (int m = 0; m < 4; ++m)
; #pragma unroll
;                     for (int n = 0; n < 2; ++n) acc[a][b][m][n] = (f32x4){0.f, 0.f, 0.f, 0.f};
;         pm = npm; pn = npn; cA = nA; cB = nB; it = itn; ++cnt;
;         if (wr == 1) BAR;
;     }
	v_mul_f32_e32 v12, v32, v12
	v_cvt_pk_bf16_f32 v12, v12, s0
	global_store_short v[16:17], v12, off
	v_and_b32_e32 v12, 0xffff0000, v224
	v_rcp_f32_e32 v20, v22
	s_nop 0
	v_mul_f32_e32 v13, v13, v20
	v_mul_f32_e32 v20, 0xbfb8aa3b, v14
	v_exp_f32_e32 v20, v20
	v_mul_f32_e32 v12, v13, v12
	v_mul_f32_e32 v12, v33, v12
	v_cvt_pk_bf16_f32 v22, v12, s0
	v_add_f32_e32 v20, 1.0, v20
	v_add_co_u32_e32 v12, vcc, s3, v16
	s_nop 0
	s_nop 0
	v_addc_co_u32_e32 v13, vcc, 0, v17, vcc
	v_mul_f32_e32 v27, 0xbfb8aa3b, v15
	v_exp_f32_e32 v27, v27
	global_store_short v[12:13], v22, off offset:-4096
	v_lshlrev_b32_e32 v22, 16, v225
	v_rcp_f32_e32 v23, v20
	s_nop 0
	v_mul_f32_e32 v14, v14, v23
	v_add_f32_e32 v20, 1.0, v27
	v_mul_f32_e32 v14, v14, v22
	v_mul_f32_e32 v14, v34, v14
	v_cvt_pk_bf16_f32 v14, v14, s0
	global_store_short v[12:13], v14, off
	v_and_b32_e32 v14, 0xffff0000, v225
	v_rcp_f32_e32 v21, v20
	s_nop 0
	v_mul_f32_e32 v15, v15, v21
	v_mul_f32_e32 v14, v15, v14
	v_mul_f32_e32 v14, v35, v14
	v_cvt_pk_bf16_f32 v20, v14, s0
	v_add_co_u32_e32 v14, vcc, s69, v16
	s_nop 1
	v_addc_co_u32_e32 v15, vcc, 0, v17, vcc
	global_store_short v[14:15], v20, off
	v_add_u32_e32 v20, v24, v126
	v_or3_b32 v20, v20, v149, v25
	v_ashrrev_i32_e32 v21, 31, v20
	v_lshlrev_b64 v[20:21], 6, v[20:21]
	v_or3_b32 v20, v20, v26, v127
	v_lshl_add_u64 v[20:21], v[20:21], 4, v[18:19]
	v_mul_f32_e32 v20, 0xbfb8aa3b, v8
	v_exp_f32_e32 v20, v20
	s_waitcnt vmcnt(22)
	v_lshlrev_b32_e32 v30, 16, v226
	v_add_f32_e32 v27, 1.0, v20
	v_add_co_u32_e32 v20, vcc, s61, v16
	s_nop 0
	s_nop 0
	v_addc_co_u32_e32 v21, vcc, 0, v17, vcc
	v_mul_f32_e32 v29, 0xbfb8aa3b, v9
	v_exp_f32_e32 v29, v29
	v_rcp_f32_e32 v28, v27
	s_nop 0
	v_mul_f32_e32 v8, v8, v28
	v_mul_f32_e32 v8, v8, v30
	v_mul_f32_e32 v8, v32, v8
	v_add_f32_e32 v27, 1.0, v29
	v_cvt_pk_bf16_f32 v8, v8, s0
	global_store_short v[16:17], v8, off offset:32
	v_and_b32_e32 v8, 0xffff0000, v226
	v_mul_f32_e32 v28, 0xbfb8aa3b, v10
	v_exp_f32_e32 v28, v28
	v_rcp_f32_e32 v22, v27
	s_nop 0
	v_mul_f32_e32 v9, v9, v22
	v_mul_f32_e32 v8, v9, v8
	v_add_f32_e32 v9, 1.0, v28
	v_mul_f32_e32 v8, v33, v8
	v_cvt_pk_bf16_f32 v8, v8, s0
	global_store_short v[20:21], v8, off offset:32
	v_mul_f32_e32 v27, 0xbfb8aa3b, v11
	v_exp_f32_e32 v27, v27
	v_lshlrev_b32_e32 v8, 16, v227
	v_rcp_f32_e32 v22, v9
	s_nop 0
	v_mul_f32_e32 v9, v10, v22
	v_mul_f32_e32 v8, v9, v8
	v_add_f32_e32 v9, 1.0, v27
	v_mul_f32_e32 v8, v34, v8
	v_cvt_pk_bf16_f32 v8, v8, s0
	global_store_short v[12:13], v8, off offset:32
	v_and_b32_e32 v8, 0xffff0000, v227
	v_rcp_f32_e32 v10, v9
	s_nop 0
	v_mul_f32_e32 v9, v11, v10
	v_mul_f32_e32 v8, v9, v8
	v_mul_f32_e32 v8, v35, v8
	v_cvt_pk_bf16_f32 v8, v8, s0
	global_store_short v[14:15], v8, off offset:32
	v_add_u32_e32 v8, v24, v121
	v_or3_b32 v8, v8, v122, v25
	v_ashrrev_i32_e32 v9, 31, v8
	v_lshlrev_b64 v[8:9], 6, v[8:9]
	v_or3_b32 v8, v8, v26, v191
	v_lshl_add_u64 v[8:9], v[8:9], 4, v[18:19]
	v_mul_f32_e32 v10, 0xbfb8aa3b, v4
	v_exp_f32_e32 v10, v10
	s_waitcnt vmcnt(21)
	v_lshlrev_b32_e32 v23, 16, v216
	v_add_f32_e32 v10, 1.0, v10
	s_nop 0
	v_mul_f32_e32 v22, 0xbfb8aa3b, v5
	v_exp_f32_e32 v22, v22
	v_rcp_f32_e32 v11, v10
	s_nop 0
	v_mul_f32_e32 v4, v4, v11
	v_mul_f32_e32 v4, v4, v23
	v_mul_f32_e32 v4, v32, v4
	v_add_f32_e32 v10, 1.0, v22
	v_cvt_pk_bf16_f32 v4, v4, s0
	global_store_short v[16:17], v4, off offset:256
	v_and_b32_e32 v4, 0xffff0000, v216
	v_mul_f32_e32 v11, 0xbfb8aa3b, v6
	v_exp_f32_e32 v11, v11
	v_rcp_f32_e32 v8, v10
	s_nop 0
	v_mul_f32_e32 v5, v5, v8
	v_mul_f32_e32 v4, v5, v4
	v_add_f32_e32 v5, 1.0, v11
	v_mul_f32_e32 v4, v33, v4
	v_cvt_pk_bf16_f32 v4, v4, s0
	global_store_short v[20:21], v4, off offset:256
	v_mul_f32_e32 v10, 0xbfb8aa3b, v7
	v_exp_f32_e32 v10, v10
	v_lshlrev_b32_e32 v4, 16, v217
	v_rcp_f32_e32 v8, v5
	s_nop 0
	v_mul_f32_e32 v5, v6, v8
	v_mul_f32_e32 v4, v5, v4
	v_add_f32_e32 v5, 1.0, v10
	v_mul_f32_e32 v4, v34, v4
	v_cvt_pk_bf16_f32 v4, v4, s0
	global_store_short v[12:13], v4, off offset:256
	v_and_b32_e32 v4, 0xffff0000, v217
	v_rcp_f32_e32 v6, v5
	s_nop 0
	v_mul_f32_e32 v5, v7, v6
	v_mul_f32_e32 v4, v5, v4
	v_mul_f32_e32 v4, v35, v4
	v_cvt_pk_bf16_f32 v4, v4, s0
	global_store_short v[14:15], v4, off offset:256
	v_add_u32_e32 v4, v24, v118
	v_or3_b32 v4, v4, v120, v25
	v_ashrrev_i32_e32 v5, 31, v4
	v_lshlrev_b64 v[4:5], 6, v[4:5]
	v_or3_b32 v4, v4, v26, v119
	v_lshl_add_u64 v[4:5], v[4:5], 4, v[18:19]
	v_mul_f32_e32 v6, 0xbfb8aa3b, v0
	v_exp_f32_e32 v6, v6
	s_waitcnt vmcnt(20)
	v_lshlrev_b32_e32 v9, 16, v218
	v_add_f32_e32 v6, 1.0, v6
	s_nop 0
	v_mul_f32_e32 v8, 0xbfb8aa3b, v1
	v_exp_f32_e32 v8, v8
	v_rcp_f32_e32 v7, v6
	s_nop 0
	v_mul_f32_e32 v0, v0, v7
	v_mul_f32_e32 v0, v0, v9
	v_mul_f32_e32 v0, v32, v0
	v_add_f32_e32 v6, 1.0, v8
	v_cvt_pk_bf16_f32 v0, v0, s0
	global_store_short v[16:17], v0, off offset:288
	v_and_b32_e32 v0, 0xffff0000, v218
	v_mul_f32_e32 v7, 0xbfb8aa3b, v2
	v_exp_f32_e32 v7, v7
	v_rcp_f32_e32 v4, v6
	s_nop 0
	v_mul_f32_e32 v1, v1, v4
	v_mul_f32_e32 v0, v1, v0
	v_add_f32_e32 v1, 1.0, v7
	v_mul_f32_e32 v0, v33, v0
	v_cvt_pk_bf16_f32 v0, v0, s0
	global_store_short v[20:21], v0, off offset:288
	v_mul_f32_e32 v6, 0xbfb8aa3b, v3
	v_exp_f32_e32 v6, v6
	v_lshlrev_b32_e32 v0, 16, v219
	v_rcp_f32_e32 v4, v1
	s_nop 0
	v_mul_f32_e32 v1, v2, v4
	v_mul_f32_e32 v0, v1, v0
	v_add_f32_e32 v1, 1.0, v6
	v_mul_f32_e32 v0, v34, v0
	v_cvt_pk_bf16_f32 v0, v0, s0
	global_store_short v[12:13], v0, off offset:288
	v_and_b32_e32 v0, 0xffff0000, v219
	v_rcp_f32_e32 v2, v1
	s_nop 0
	v_mul_f32_e32 v1, v3, v2
	v_mul_f32_e32 v0, v1, v0
	v_mul_f32_e32 v0, v35, v0
	v_cvt_pk_bf16_f32 v0, v0, s0
	s_andn2_b64 vcc, exec, s[28:29]
	s_mov_b64 s[10:11], -1
	global_store_short v[14:15], v0, off offset:288
	s_cbranch_vccnz .LBB0_1626
	s_and_saveexec_b64 s[10:11], s[6:7]
	s_xor_b64 s[10:11], exec, s[10:11]
	s_cbranch_execz .LBB0_1625
	s_barrier
	s_branch .LBB0_1625
